# phase 0 GEMV fully unrolled with a rolling window of 32 weight loads in flight (no per-trip drain)
# baseline (speedup 1.0000x reference)
.LBB0_19:
	s_mul_i32 s12, s1, 0x1800
	v_lshl_add_u64 v[32:33], s[12:13], 2, v[14:15]
	s_add_i32 s3, s1, s36
	s_mulk_i32 s3, 0x50
	v_mov_b32_e32 v5, s3
	s_mov_b32 s6, 0x6000
	s_mov_b32 s7, 0
	ds_read_b128 v[144:147], v5
	ds_read_b128 v[148:151], v5 offset:16
	ds_read_b128 v[152:155], v5 offset:32
	ds_read_b128 v[156:159], v5 offset:48
	ds_read_b32 v192, v5 offset:64
	ds_read_b128 v[160:163], v5 offset:80
	ds_read_b128 v[164:167], v5 offset:96
	ds_read_b128 v[168:171], v5 offset:112
	ds_read_b128 v[172:175], v5 offset:128
	ds_read_b32 v193, v5 offset:144
	global_load_dword v80, v[32:33], off
	v_lshl_add_u64 v[32:33], v[32:33], 0, s[6:7]
	global_load_dword v82, v[32:33], off
	v_lshl_add_u64 v[32:33], v[32:33], 0, s[6:7]
	global_load_dword v84, v[32:33], off
	v_lshl_add_u64 v[32:33], v[32:33], 0, s[6:7]
	global_load_dword v86, v[32:33], off
	v_lshl_add_u64 v[32:33], v[32:33], 0, s[6:7]
	global_load_dword v88, v[32:33], off
	v_lshl_add_u64 v[32:33], v[32:33], 0, s[6:7]
	global_load_dword v90, v[32:33], off
	v_lshl_add_u64 v[32:33], v[32:33], 0, s[6:7]
	global_load_dword v92, v[32:33], off
	v_lshl_add_u64 v[32:33], v[32:33], 0, s[6:7]
	global_load_dword v94, v[32:33], off
	v_lshl_add_u64 v[32:33], v[32:33], 0, s[6:7]
	global_load_dword v96, v[32:33], off
	v_lshl_add_u64 v[32:33], v[32:33], 0, s[6:7]
	global_load_dword v98, v[32:33], off
	v_lshl_add_u64 v[32:33], v[32:33], 0, s[6:7]
	global_load_dword v100, v[32:33], off
	v_lshl_add_u64 v[32:33], v[32:33], 0, s[6:7]
	global_load_dword v102, v[32:33], off
	v_lshl_add_u64 v[32:33], v[32:33], 0, s[6:7]
	global_load_dword v104, v[32:33], off
	v_lshl_add_u64 v[32:33], v[32:33], 0, s[6:7]
	global_load_dword v106, v[32:33], off
	v_lshl_add_u64 v[32:33], v[32:33], 0, s[6:7]
	global_load_dword v108, v[32:33], off
	v_lshl_add_u64 v[32:33], v[32:33], 0, s[6:7]
	global_load_dword v110, v[32:33], off
	v_lshl_add_u64 v[32:33], v[32:33], 0, s[6:7]
	global_load_dword v112, v[32:33], off
	v_lshl_add_u64 v[32:33], v[32:33], 0, s[6:7]
	global_load_dword v114, v[32:33], off
	v_lshl_add_u64 v[32:33], v[32:33], 0, s[6:7]
	global_load_dword v116, v[32:33], off
	v_lshl_add_u64 v[32:33], v[32:33], 0, s[6:7]
	global_load_dword v118, v[32:33], off
	v_lshl_add_u64 v[32:33], v[32:33], 0, s[6:7]
	global_load_dword v120, v[32:33], off
	v_lshl_add_u64 v[32:33], v[32:33], 0, s[6:7]
	global_load_dword v122, v[32:33], off
	v_lshl_add_u64 v[32:33], v[32:33], 0, s[6:7]
	global_load_dword v124, v[32:33], off
	v_lshl_add_u64 v[32:33], v[32:33], 0, s[6:7]
	global_load_dword v126, v[32:33], off
	v_lshl_add_u64 v[32:33], v[32:33], 0, s[6:7]
	global_load_dword v128, v[32:33], off
	v_lshl_add_u64 v[32:33], v[32:33], 0, s[6:7]
	global_load_dword v130, v[32:33], off
	v_lshl_add_u64 v[32:33], v[32:33], 0, s[6:7]
	global_load_dword v132, v[32:33], off
	v_lshl_add_u64 v[32:33], v[32:33], 0, s[6:7]
	global_load_dword v134, v[32:33], off
	v_lshl_add_u64 v[32:33], v[32:33], 0, s[6:7]
	global_load_dword v136, v[32:33], off
	v_lshl_add_u64 v[32:33], v[32:33], 0, s[6:7]
	global_load_dword v138, v[32:33], off
	v_lshl_add_u64 v[32:33], v[32:33], 0, s[6:7]
	global_load_dword v140, v[32:33], off
	v_lshl_add_u64 v[32:33], v[32:33], 0, s[6:7]
	global_load_dword v142, v[32:33], off
	ds_read_b128 v[176:179], v5 offset:160
	ds_read_b128 v[180:183], v5 offset:176
	ds_read_b128 v[184:187], v5 offset:192
	ds_read_b128 v[188:191], v5 offset:208
	ds_read_b32 v194, v5 offset:224
	s_waitcnt vmcnt(31) lgkmcnt(10)
	v_pk_fma_f32 v[16:17], v[80:81], v[144:145], v[16:17] op_sel_hi:[0,1,1]
	v_pk_fma_f32 v[18:19], v[80:81], v[146:147], v[18:19] op_sel_hi:[0,1,1]
	v_pk_fma_f32 v[20:21], v[80:81], v[148:149], v[20:21] op_sel_hi:[0,1,1]
	v_pk_fma_f32 v[22:23], v[80:81], v[150:151], v[22:23] op_sel_hi:[0,1,1]
	v_pk_fma_f32 v[24:25], v[80:81], v[152:153], v[24:25] op_sel_hi:[0,1,1]
	v_pk_fma_f32 v[26:27], v[80:81], v[154:155], v[26:27] op_sel_hi:[0,1,1]
	v_pk_fma_f32 v[28:29], v[80:81], v[156:157], v[28:29] op_sel_hi:[0,1,1]
	v_pk_fma_f32 v[30:31], v[80:81], v[158:159], v[30:31] op_sel_hi:[0,1,1]
	v_fmac_f32_e32 v2, v80, v192
	v_lshl_add_u64 v[32:33], v[32:33], 0, s[6:7]
	global_load_dword v80, v[32:33], off
	ds_read_b128 v[144:147], v5 offset:240
	ds_read_b128 v[148:151], v5 offset:256
	ds_read_b128 v[152:155], v5 offset:272
	ds_read_b128 v[156:159], v5 offset:288
	ds_read_b32 v192, v5 offset:304
	s_waitcnt vmcnt(31) lgkmcnt(10)
	v_pk_fma_f32 v[16:17], v[82:83], v[160:161], v[16:17] op_sel_hi:[0,1,1]
	v_pk_fma_f32 v[18:19], v[82:83], v[162:163], v[18:19] op_sel_hi:[0,1,1]
	v_pk_fma_f32 v[20:21], v[82:83], v[164:165], v[20:21] op_sel_hi:[0,1,1]
	v_pk_fma_f32 v[22:23], v[82:83], v[166:167], v[22:23] op_sel_hi:[0,1,1]
	v_pk_fma_f32 v[24:25], v[82:83], v[168:169], v[24:25] op_sel_hi:[0,1,1]
	v_pk_fma_f32 v[26:27], v[82:83], v[170:171], v[26:27] op_sel_hi:[0,1,1]
	v_pk_fma_f32 v[28:29], v[82:83], v[172:173], v[28:29] op_sel_hi:[0,1,1]
	v_pk_fma_f32 v[30:31], v[82:83], v[174:175], v[30:31] op_sel_hi:[0,1,1]
	v_fmac_f32_e32 v2, v82, v193
	v_lshl_add_u64 v[32:33], v[32:33], 0, s[6:7]
	global_load_dword v82, v[32:33], off
	ds_read_b128 v[160:163], v5 offset:320
	ds_read_b128 v[164:167], v5 offset:336
	ds_read_b128 v[168:171], v5 offset:352
	ds_read_b128 v[172:175], v5 offset:368
	ds_read_b32 v193, v5 offset:384
	s_waitcnt vmcnt(31) lgkmcnt(10)
	v_pk_fma_f32 v[16:17], v[84:85], v[176:177], v[16:17] op_sel_hi:[0,1,1]
	v_pk_fma_f32 v[18:19], v[84:85], v[178:179], v[18:19] op_sel_hi:[0,1,1]
	v_pk_fma_f32 v[20:21], v[84:85], v[180:181], v[20:21] op_sel_hi:[0,1,1]
	v_pk_fma_f32 v[22:23], v[84:85], v[182:183], v[22:23] op_sel_hi:[0,1,1]
	v_pk_fma_f32 v[24:25], v[84:85], v[184:185], v[24:25] op_sel_hi:[0,1,1]
	v_pk_fma_f32 v[26:27], v[84:85], v[186:187], v[26:27] op_sel_hi:[0,1,1]
	v_pk_fma_f32 v[28:29], v[84:85], v[188:189], v[28:29] op_sel_hi:[0,1,1]
	v_pk_fma_f32 v[30:31], v[84:85], v[190:191], v[30:31] op_sel_hi:[0,1,1]
	v_fmac_f32_e32 v2, v84, v194
	v_lshl_add_u64 v[32:33], v[32:33], 0, s[6:7]
	global_load_dword v84, v[32:33], off
	ds_read_b128 v[176:179], v5 offset:400
	ds_read_b128 v[180:183], v5 offset:416
	ds_read_b128 v[184:187], v5 offset:432
	ds_read_b128 v[188:191], v5 offset:448
	ds_read_b32 v194, v5 offset:464
	s_waitcnt vmcnt(31) lgkmcnt(10)
	v_pk_fma_f32 v[16:17], v[86:87], v[144:145], v[16:17] op_sel_hi:[0,1,1]
	v_pk_fma_f32 v[18:19], v[86:87], v[146:147], v[18:19] op_sel_hi:[0,1,1]
	v_pk_fma_f32 v[20:21], v[86:87], v[148:149], v[20:21] op_sel_hi:[0,1,1]
	v_pk_fma_f32 v[22:23], v[86:87], v[150:151], v[22:23] op_sel_hi:[0,1,1]
	v_pk_fma_f32 v[24:25], v[86:87], v[152:153], v[24:25] op_sel_hi:[0,1,1]
	v_pk_fma_f32 v[26:27], v[86:87], v[154:155], v[26:27] op_sel_hi:[0,1,1]
	v_pk_fma_f32 v[28:29], v[86:87], v[156:157], v[28:29] op_sel_hi:[0,1,1]
	v_pk_fma_f32 v[30:31], v[86:87], v[158:159], v[30:31] op_sel_hi:[0,1,1]
	v_fmac_f32_e32 v2, v86, v192
	v_lshl_add_u64 v[32:33], v[32:33], 0, s[6:7]
	global_load_dword v86, v[32:33], off
	ds_read_b128 v[144:147], v5 offset:480
	ds_read_b128 v[148:151], v5 offset:496
	ds_read_b128 v[152:155], v5 offset:512
	ds_read_b128 v[156:159], v5 offset:528
	ds_read_b32 v192, v5 offset:544
	s_waitcnt vmcnt(31) lgkmcnt(10)
	v_pk_fma_f32 v[16:17], v[88:89], v[160:161], v[16:17] op_sel_hi:[0,1,1]
	v_pk_fma_f32 v[18:19], v[88:89], v[162:163], v[18:19] op_sel_hi:[0,1,1]
	v_pk_fma_f32 v[20:21], v[88:89], v[164:165], v[20:21] op_sel_hi:[0,1,1]
	v_pk_fma_f32 v[22:23], v[88:89], v[166:167], v[22:23] op_sel_hi:[0,1,1]
	v_pk_fma_f32 v[24:25], v[88:89], v[168:169], v[24:25] op_sel_hi:[0,1,1]
	v_pk_fma_f32 v[26:27], v[88:89], v[170:171], v[26:27] op_sel_hi:[0,1,1]
	v_pk_fma_f32 v[28:29], v[88:89], v[172:173], v[28:29] op_sel_hi:[0,1,1]
	v_pk_fma_f32 v[30:31], v[88:89], v[174:175], v[30:31] op_sel_hi:[0,1,1]
	v_fmac_f32_e32 v2, v88, v193
	v_lshl_add_u64 v[32:33], v[32:33], 0, s[6:7]
	global_load_dword v88, v[32:33], off
	ds_read_b128 v[160:163], v5 offset:560
	ds_read_b128 v[164:167], v5 offset:576
	ds_read_b128 v[168:171], v5 offset:592
	ds_read_b128 v[172:175], v5 offset:608
	ds_read_b32 v193, v5 offset:624
	s_waitcnt vmcnt(31) lgkmcnt(10)
	v_pk_fma_f32 v[16:17], v[90:91], v[176:177], v[16:17] op_sel_hi:[0,1,1]
	v_pk_fma_f32 v[18:19], v[90:91], v[178:179], v[18:19] op_sel_hi:[0,1,1]
	v_pk_fma_f32 v[20:21], v[90:91], v[180:181], v[20:21] op_sel_hi:[0,1,1]
	v_pk_fma_f32 v[22:23], v[90:91], v[182:183], v[22:23] op_sel_hi:[0,1,1]
	v_pk_fma_f32 v[24:25], v[90:91], v[184:185], v[24:25] op_sel_hi:[0,1,1]
	v_pk_fma_f32 v[26:27], v[90:91], v[186:187], v[26:27] op_sel_hi:[0,1,1]
	v_pk_fma_f32 v[28:29], v[90:91], v[188:189], v[28:29] op_sel_hi:[0,1,1]
	v_pk_fma_f32 v[30:31], v[90:91], v[190:191], v[30:31] op_sel_hi:[0,1,1]
	v_fmac_f32_e32 v2, v90, v194
	v_lshl_add_u64 v[32:33], v[32:33], 0, s[6:7]
	global_load_dword v90, v[32:33], off
	ds_read_b128 v[176:179], v5 offset:640
	ds_read_b128 v[180:183], v5 offset:656
	ds_read_b128 v[184:187], v5 offset:672
	ds_read_b128 v[188:191], v5 offset:688
	ds_read_b32 v194, v5 offset:704
	s_waitcnt vmcnt(31) lgkmcnt(10)
	v_pk_fma_f32 v[16:17], v[92:93], v[144:145], v[16:17] op_sel_hi:[0,1,1]
	v_pk_fma_f32 v[18:19], v[92:93], v[146:147], v[18:19] op_sel_hi:[0,1,1]
	v_pk_fma_f32 v[20:21], v[92:93], v[148:149], v[20:21] op_sel_hi:[0,1,1]
	v_pk_fma_f32 v[22:23], v[92:93], v[150:151], v[22:23] op_sel_hi:[0,1,1]
	v_pk_fma_f32 v[24:25], v[92:93], v[152:153], v[24:25] op_sel_hi:[0,1,1]
	v_pk_fma_f32 v[26:27], v[92:93], v[154:155], v[26:27] op_sel_hi:[0,1,1]
	v_pk_fma_f32 v[28:29], v[92:93], v[156:157], v[28:29] op_sel_hi:[0,1,1]
	v_pk_fma_f32 v[30:31], v[92:93], v[158:159], v[30:31] op_sel_hi:[0,1,1]
	v_fmac_f32_e32 v2, v92, v192
	v_lshl_add_u64 v[32:33], v[32:33], 0, s[6:7]
	global_load_dword v92, v[32:33], off
	ds_read_b128 v[144:147], v5 offset:720
	ds_read_b128 v[148:151], v5 offset:736
	ds_read_b128 v[152:155], v5 offset:752
	ds_read_b128 v[156:159], v5 offset:768
	ds_read_b32 v192, v5 offset:784
	s_waitcnt vmcnt(31) lgkmcnt(10)
	v_pk_fma_f32 v[16:17], v[94:95], v[160:161], v[16:17] op_sel_hi:[0,1,1]
	v_pk_fma_f32 v[18:19], v[94:95], v[162:163], v[18:19] op_sel_hi:[0,1,1]
	v_pk_fma_f32 v[20:21], v[94:95], v[164:165], v[20:21] op_sel_hi:[0,1,1]
	v_pk_fma_f32 v[22:23], v[94:95], v[166:167], v[22:23] op_sel_hi:[0,1,1]
	v_pk_fma_f32 v[24:25], v[94:95], v[168:169], v[24:25] op_sel_hi:[0,1,1]
	v_pk_fma_f32 v[26:27], v[94:95], v[170:171], v[26:27] op_sel_hi:[0,1,1]
	v_pk_fma_f32 v[28:29], v[94:95], v[172:173], v[28:29] op_sel_hi:[0,1,1]
	v_pk_fma_f32 v[30:31], v[94:95], v[174:175], v[30:31] op_sel_hi:[0,1,1]
	v_fmac_f32_e32 v2, v94, v193
	v_lshl_add_u64 v[32:33], v[32:33], 0, s[6:7]
	global_load_dword v94, v[32:33], off
	ds_read_b128 v[160:163], v5 offset:800
	ds_read_b128 v[164:167], v5 offset:816
	ds_read_b128 v[168:171], v5 offset:832
	ds_read_b128 v[172:175], v5 offset:848
	ds_read_b32 v193, v5 offset:864
	s_waitcnt vmcnt(31) lgkmcnt(10)
	v_pk_fma_f32 v[16:17], v[96:97], v[176:177], v[16:17] op_sel_hi:[0,1,1]
	v_pk_fma_f32 v[18:19], v[96:97], v[178:179], v[18:19] op_sel_hi:[0,1,1]
	v_pk_fma_f32 v[20:21], v[96:97], v[180:181], v[20:21] op_sel_hi:[0,1,1]
	v_pk_fma_f32 v[22:23], v[96:97], v[182:183], v[22:23] op_sel_hi:[0,1,1]
	v_pk_fma_f32 v[24:25], v[96:97], v[184:185], v[24:25] op_sel_hi:[0,1,1]
	v_pk_fma_f32 v[26:27], v[96:97], v[186:187], v[26:27] op_sel_hi:[0,1,1]
	v_pk_fma_f32 v[28:29], v[96:97], v[188:189], v[28:29] op_sel_hi:[0,1,1]
	v_pk_fma_f32 v[30:31], v[96:97], v[190:191], v[30:31] op_sel_hi:[0,1,1]
	v_fmac_f32_e32 v2, v96, v194
	v_lshl_add_u64 v[32:33], v[32:33], 0, s[6:7]
	global_load_dword v96, v[32:33], off
	ds_read_b128 v[176:179], v5 offset:880
	ds_read_b128 v[180:183], v5 offset:896
	ds_read_b128 v[184:187], v5 offset:912
	ds_read_b128 v[188:191], v5 offset:928
	ds_read_b32 v194, v5 offset:944
	s_waitcnt vmcnt(31) lgkmcnt(10)
	v_pk_fma_f32 v[16:17], v[98:99], v[144:145], v[16:17] op_sel_hi:[0,1,1]
	v_pk_fma_f32 v[18:19], v[98:99], v[146:147], v[18:19] op_sel_hi:[0,1,1]
	v_pk_fma_f32 v[20:21], v[98:99], v[148:149], v[20:21] op_sel_hi:[0,1,1]
	v_pk_fma_f32 v[22:23], v[98:99], v[150:151], v[22:23] op_sel_hi:[0,1,1]
	v_pk_fma_f32 v[24:25], v[98:99], v[152:153], v[24:25] op_sel_hi:[0,1,1]
	v_pk_fma_f32 v[26:27], v[98:99], v[154:155], v[26:27] op_sel_hi:[0,1,1]
	v_pk_fma_f32 v[28:29], v[98:99], v[156:157], v[28:29] op_sel_hi:[0,1,1]
	v_pk_fma_f32 v[30:31], v[98:99], v[158:159], v[30:31] op_sel_hi:[0,1,1]
	v_fmac_f32_e32 v2, v98, v192
	v_lshl_add_u64 v[32:33], v[32:33], 0, s[6:7]
	global_load_dword v98, v[32:33], off
	ds_read_b128 v[144:147], v5 offset:960
	ds_read_b128 v[148:151], v5 offset:976
	ds_read_b128 v[152:155], v5 offset:992
	ds_read_b128 v[156:159], v5 offset:1008
	ds_read_b32 v192, v5 offset:1024
	s_waitcnt vmcnt(31) lgkmcnt(10)
	v_pk_fma_f32 v[16:17], v[100:101], v[160:161], v[16:17] op_sel_hi:[0,1,1]
	v_pk_fma_f32 v[18:19], v[100:101], v[162:163], v[18:19] op_sel_hi:[0,1,1]
	v_pk_fma_f32 v[20:21], v[100:101], v[164:165], v[20:21] op_sel_hi:[0,1,1]
	v_pk_fma_f32 v[22:23], v[100:101], v[166:167], v[22:23] op_sel_hi:[0,1,1]
	v_pk_fma_f32 v[24:25], v[100:101], v[168:169], v[24:25] op_sel_hi:[0,1,1]
	v_pk_fma_f32 v[26:27], v[100:101], v[170:171], v[26:27] op_sel_hi:[0,1,1]
	v_pk_fma_f32 v[28:29], v[100:101], v[172:173], v[28:29] op_sel_hi:[0,1,1]
	v_pk_fma_f32 v[30:31], v[100:101], v[174:175], v[30:31] op_sel_hi:[0,1,1]
	v_fmac_f32_e32 v2, v100, v193
	v_lshl_add_u64 v[32:33], v[32:33], 0, s[6:7]
	global_load_dword v100, v[32:33], off
	ds_read_b128 v[160:163], v5 offset:1040
	ds_read_b128 v[164:167], v5 offset:1056
	ds_read_b128 v[168:171], v5 offset:1072
	ds_read_b128 v[172:175], v5 offset:1088
	ds_read_b32 v193, v5 offset:1104
	s_waitcnt vmcnt(31) lgkmcnt(10)
	v_pk_fma_f32 v[16:17], v[102:103], v[176:177], v[16:17] op_sel_hi:[0,1,1]
	v_pk_fma_f32 v[18:19], v[102:103], v[178:179], v[18:19] op_sel_hi:[0,1,1]
	v_pk_fma_f32 v[20:21], v[102:103], v[180:181], v[20:21] op_sel_hi:[0,1,1]
	v_pk_fma_f32 v[22:23], v[102:103], v[182:183], v[22:23] op_sel_hi:[0,1,1]
	v_pk_fma_f32 v[24:25], v[102:103], v[184:185], v[24:25] op_sel_hi:[0,1,1]
	v_pk_fma_f32 v[26:27], v[102:103], v[186:187], v[26:27] op_sel_hi:[0,1,1]
	v_pk_fma_f32 v[28:29], v[102:103], v[188:189], v[28:29] op_sel_hi:[0,1,1]
	v_pk_fma_f32 v[30:31], v[102:103], v[190:191], v[30:31] op_sel_hi:[0,1,1]
	v_fmac_f32_e32 v2, v102, v194
	v_lshl_add_u64 v[32:33], v[32:33], 0, s[6:7]
	global_load_dword v102, v[32:33], off
	ds_read_b128 v[176:179], v5 offset:1120
	ds_read_b128 v[180:183], v5 offset:1136
	ds_read_b128 v[184:187], v5 offset:1152
	ds_read_b128 v[188:191], v5 offset:1168
	ds_read_b32 v194, v5 offset:1184
	s_waitcnt vmcnt(31) lgkmcnt(10)
	v_pk_fma_f32 v[16:17], v[104:105], v[144:145], v[16:17] op_sel_hi:[0,1,1]
	v_pk_fma_f32 v[18:19], v[104:105], v[146:147], v[18:19] op_sel_hi:[0,1,1]
	v_pk_fma_f32 v[20:21], v[104:105], v[148:149], v[20:21] op_sel_hi:[0,1,1]
	v_pk_fma_f32 v[22:23], v[104:105], v[150:151], v[22:23] op_sel_hi:[0,1,1]
	v_pk_fma_f32 v[24:25], v[104:105], v[152:153], v[24:25] op_sel_hi:[0,1,1]
	v_pk_fma_f32 v[26:27], v[104:105], v[154:155], v[26:27] op_sel_hi:[0,1,1]
	v_pk_fma_f32 v[28:29], v[104:105], v[156:157], v[28:29] op_sel_hi:[0,1,1]
	v_pk_fma_f32 v[30:31], v[104:105], v[158:159], v[30:31] op_sel_hi:[0,1,1]
	v_fmac_f32_e32 v2, v104, v192
	v_lshl_add_u64 v[32:33], v[32:33], 0, s[6:7]
	global_load_dword v104, v[32:33], off
	ds_read_b128 v[144:147], v5 offset:1200
	ds_read_b128 v[148:151], v5 offset:1216
	ds_read_b128 v[152:155], v5 offset:1232
	ds_read_b128 v[156:159], v5 offset:1248
	ds_read_b32 v192, v5 offset:1264
	s_waitcnt vmcnt(31) lgkmcnt(10)
	v_pk_fma_f32 v[16:17], v[106:107], v[160:161], v[16:17] op_sel_hi:[0,1,1]
	v_pk_fma_f32 v[18:19], v[106:107], v[162:163], v[18:19] op_sel_hi:[0,1,1]
	v_pk_fma_f32 v[20:21], v[106:107], v[164:165], v[20:21] op_sel_hi:[0,1,1]
	v_pk_fma_f32 v[22:23], v[106:107], v[166:167], v[22:23] op_sel_hi:[0,1,1]
	v_pk_fma_f32 v[24:25], v[106:107], v[168:169], v[24:25] op_sel_hi:[0,1,1]
	v_pk_fma_f32 v[26:27], v[106:107], v[170:171], v[26:27] op_sel_hi:[0,1,1]
	v_pk_fma_f32 v[28:29], v[106:107], v[172:173], v[28:29] op_sel_hi:[0,1,1]
	v_pk_fma_f32 v[30:31], v[106:107], v[174:175], v[30:31] op_sel_hi:[0,1,1]
	v_fmac_f32_e32 v2, v106, v193
	v_lshl_add_u64 v[32:33], v[32:33], 0, s[6:7]
	global_load_dword v106, v[32:33], off
	ds_read_b128 v[160:163], v5 offset:1280
	ds_read_b128 v[164:167], v5 offset:1296
	ds_read_b128 v[168:171], v5 offset:1312
	ds_read_b128 v[172:175], v5 offset:1328
	ds_read_b32 v193, v5 offset:1344
	s_waitcnt vmcnt(31) lgkmcnt(10)
	v_pk_fma_f32 v[16:17], v[108:109], v[176:177], v[16:17] op_sel_hi:[0,1,1]
	v_pk_fma_f32 v[18:19], v[108:109], v[178:179], v[18:19] op_sel_hi:[0,1,1]
	v_pk_fma_f32 v[20:21], v[108:109], v[180:181], v[20:21] op_sel_hi:[0,1,1]
	v_pk_fma_f32 v[22:23], v[108:109], v[182:183], v[22:23] op_sel_hi:[0,1,1]
	v_pk_fma_f32 v[24:25], v[108:109], v[184:185], v[24:25] op_sel_hi:[0,1,1]
	v_pk_fma_f32 v[26:27], v[108:109], v[186:187], v[26:27] op_sel_hi:[0,1,1]
	v_pk_fma_f32 v[28:29], v[108:109], v[188:189], v[28:29] op_sel_hi:[0,1,1]
	v_pk_fma_f32 v[30:31], v[108:109], v[190:191], v[30:31] op_sel_hi:[0,1,1]
	v_fmac_f32_e32 v2, v108, v194
	v_lshl_add_u64 v[32:33], v[32:33], 0, s[6:7]
	global_load_dword v108, v[32:33], off
	ds_read_b128 v[176:179], v5 offset:1360
	ds_read_b128 v[180:183], v5 offset:1376
	ds_read_b128 v[184:187], v5 offset:1392
	ds_read_b128 v[188:191], v5 offset:1408
	ds_read_b32 v194, v5 offset:1424
	s_waitcnt vmcnt(31) lgkmcnt(10)
	v_pk_fma_f32 v[16:17], v[110:111], v[144:145], v[16:17] op_sel_hi:[0,1,1]
	v_pk_fma_f32 v[18:19], v[110:111], v[146:147], v[18:19] op_sel_hi:[0,1,1]
	v_pk_fma_f32 v[20:21], v[110:111], v[148:149], v[20:21] op_sel_hi:[0,1,1]
	v_pk_fma_f32 v[22:23], v[110:111], v[150:151], v[22:23] op_sel_hi:[0,1,1]
	v_pk_fma_f32 v[24:25], v[110:111], v[152:153], v[24:25] op_sel_hi:[0,1,1]
	v_pk_fma_f32 v[26:27], v[110:111], v[154:155], v[26:27] op_sel_hi:[0,1,1]
	v_pk_fma_f32 v[28:29], v[110:111], v[156:157], v[28:29] op_sel_hi:[0,1,1]
	v_pk_fma_f32 v[30:31], v[110:111], v[158:159], v[30:31] op_sel_hi:[0,1,1]
	v_fmac_f32_e32 v2, v110, v192
	v_lshl_add_u64 v[32:33], v[32:33], 0, s[6:7]
	global_load_dword v110, v[32:33], off
	ds_read_b128 v[144:147], v5 offset:1440
	ds_read_b128 v[148:151], v5 offset:1456
	ds_read_b128 v[152:155], v5 offset:1472
	ds_read_b128 v[156:159], v5 offset:1488
	ds_read_b32 v192, v5 offset:1504
	s_waitcnt vmcnt(31) lgkmcnt(10)
	v_pk_fma_f32 v[16:17], v[112:113], v[160:161], v[16:17] op_sel_hi:[0,1,1]
	v_pk_fma_f32 v[18:19], v[112:113], v[162:163], v[18:19] op_sel_hi:[0,1,1]
	v_pk_fma_f32 v[20:21], v[112:113], v[164:165], v[20:21] op_sel_hi:[0,1,1]
	v_pk_fma_f32 v[22:23], v[112:113], v[166:167], v[22:23] op_sel_hi:[0,1,1]
	v_pk_fma_f32 v[24:25], v[112:113], v[168:169], v[24:25] op_sel_hi:[0,1,1]
	v_pk_fma_f32 v[26:27], v[112:113], v[170:171], v[26:27] op_sel_hi:[0,1,1]
	v_pk_fma_f32 v[28:29], v[112:113], v[172:173], v[28:29] op_sel_hi:[0,1,1]
	v_pk_fma_f32 v[30:31], v[112:113], v[174:175], v[30:31] op_sel_hi:[0,1,1]
	v_fmac_f32_e32 v2, v112, v193
	v_lshl_add_u64 v[32:33], v[32:33], 0, s[6:7]
	global_load_dword v112, v[32:33], off
	ds_read_b128 v[160:163], v5 offset:1520
	ds_read_b128 v[164:167], v5 offset:1536
	ds_read_b128 v[168:171], v5 offset:1552
	ds_read_b128 v[172:175], v5 offset:1568
	ds_read_b32 v193, v5 offset:1584
	s_waitcnt vmcnt(31) lgkmcnt(10)
	v_pk_fma_f32 v[16:17], v[114:115], v[176:177], v[16:17] op_sel_hi:[0,1,1]
	v_pk_fma_f32 v[18:19], v[114:115], v[178:179], v[18:19] op_sel_hi:[0,1,1]
	v_pk_fma_f32 v[20:21], v[114:115], v[180:181], v[20:21] op_sel_hi:[0,1,1]
	v_pk_fma_f32 v[22:23], v[114:115], v[182:183], v[22:23] op_sel_hi:[0,1,1]
	v_pk_fma_f32 v[24:25], v[114:115], v[184:185], v[24:25] op_sel_hi:[0,1,1]
	v_pk_fma_f32 v[26:27], v[114:115], v[186:187], v[26:27] op_sel_hi:[0,1,1]
	v_pk_fma_f32 v[28:29], v[114:115], v[188:189], v[28:29] op_sel_hi:[0,1,1]
	v_pk_fma_f32 v[30:31], v[114:115], v[190:191], v[30:31] op_sel_hi:[0,1,1]
	v_fmac_f32_e32 v2, v114, v194
	v_lshl_add_u64 v[32:33], v[32:33], 0, s[6:7]
	global_load_dword v114, v[32:33], off
	ds_read_b128 v[176:179], v5 offset:1600
	ds_read_b128 v[180:183], v5 offset:1616
	ds_read_b128 v[184:187], v5 offset:1632
	ds_read_b128 v[188:191], v5 offset:1648
	ds_read_b32 v194, v5 offset:1664
	s_waitcnt vmcnt(31) lgkmcnt(10)
	v_pk_fma_f32 v[16:17], v[116:117], v[144:145], v[16:17] op_sel_hi:[0,1,1]
	v_pk_fma_f32 v[18:19], v[116:117], v[146:147], v[18:19] op_sel_hi:[0,1,1]
	v_pk_fma_f32 v[20:21], v[116:117], v[148:149], v[20:21] op_sel_hi:[0,1,1]
	v_pk_fma_f32 v[22:23], v[116:117], v[150:151], v[22:23] op_sel_hi:[0,1,1]
	v_pk_fma_f32 v[24:25], v[116:117], v[152:153], v[24:25] op_sel_hi:[0,1,1]
	v_pk_fma_f32 v[26:27], v[116:117], v[154:155], v[26:27] op_sel_hi:[0,1,1]
	v_pk_fma_f32 v[28:29], v[116:117], v[156:157], v[28:29] op_sel_hi:[0,1,1]
	v_pk_fma_f32 v[30:31], v[116:117], v[158:159], v[30:31] op_sel_hi:[0,1,1]
	v_fmac_f32_e32 v2, v116, v192
	v_lshl_add_u64 v[32:33], v[32:33], 0, s[6:7]
	global_load_dword v116, v[32:33], off
	ds_read_b128 v[144:147], v5 offset:1680
	ds_read_b128 v[148:151], v5 offset:1696
	ds_read_b128 v[152:155], v5 offset:1712
	ds_read_b128 v[156:159], v5 offset:1728
	ds_read_b32 v192, v5 offset:1744
	s_waitcnt vmcnt(31) lgkmcnt(10)
	v_pk_fma_f32 v[16:17], v[118:119], v[160:161], v[16:17] op_sel_hi:[0,1,1]
	v_pk_fma_f32 v[18:19], v[118:119], v[162:163], v[18:19] op_sel_hi:[0,1,1]
	v_pk_fma_f32 v[20:21], v[118:119], v[164:165], v[20:21] op_sel_hi:[0,1,1]
	v_pk_fma_f32 v[22:23], v[118:119], v[166:167], v[22:23] op_sel_hi:[0,1,1]
	v_pk_fma_f32 v[24:25], v[118:119], v[168:169], v[24:25] op_sel_hi:[0,1,1]
	v_pk_fma_f32 v[26:27], v[118:119], v[170:171], v[26:27] op_sel_hi:[0,1,1]
	v_pk_fma_f32 v[28:29], v[118:119], v[172:173], v[28:29] op_sel_hi:[0,1,1]
	v_pk_fma_f32 v[30:31], v[118:119], v[174:175], v[30:31] op_sel_hi:[0,1,1]
	v_fmac_f32_e32 v2, v118, v193
	v_lshl_add_u64 v[32:33], v[32:33], 0, s[6:7]
	global_load_dword v118, v[32:33], off
	ds_read_b128 v[160:163], v5 offset:1760
	ds_read_b128 v[164:167], v5 offset:1776
	ds_read_b128 v[168:171], v5 offset:1792
	ds_read_b128 v[172:175], v5 offset:1808
	ds_read_b32 v193, v5 offset:1824
	s_waitcnt vmcnt(31) lgkmcnt(10)
	v_pk_fma_f32 v[16:17], v[120:121], v[176:177], v[16:17] op_sel_hi:[0,1,1]
	v_pk_fma_f32 v[18:19], v[120:121], v[178:179], v[18:19] op_sel_hi:[0,1,1]
	v_pk_fma_f32 v[20:21], v[120:121], v[180:181], v[20:21] op_sel_hi:[0,1,1]
	v_pk_fma_f32 v[22:23], v[120:121], v[182:183], v[22:23] op_sel_hi:[0,1,1]
	v_pk_fma_f32 v[24:25], v[120:121], v[184:185], v[24:25] op_sel_hi:[0,1,1]
	v_pk_fma_f32 v[26:27], v[120:121], v[186:187], v[26:27] op_sel_hi:[0,1,1]
	v_pk_fma_f32 v[28:29], v[120:121], v[188:189], v[28:29] op_sel_hi:[0,1,1]
	v_pk_fma_f32 v[30:31], v[120:121], v[190:191], v[30:31] op_sel_hi:[0,1,1]
	v_fmac_f32_e32 v2, v120, v194
	v_lshl_add_u64 v[32:33], v[32:33], 0, s[6:7]
	global_load_dword v120, v[32:33], off
	ds_read_b128 v[176:179], v5 offset:1840
	ds_read_b128 v[180:183], v5 offset:1856
	ds_read_b128 v[184:187], v5 offset:1872
	ds_read_b128 v[188:191], v5 offset:1888
	ds_read_b32 v194, v5 offset:1904
	s_waitcnt vmcnt(31) lgkmcnt(10)
	v_pk_fma_f32 v[16:17], v[122:123], v[144:145], v[16:17] op_sel_hi:[0,1,1]
	v_pk_fma_f32 v[18:19], v[122:123], v[146:147], v[18:19] op_sel_hi:[0,1,1]
	v_pk_fma_f32 v[20:21], v[122:123], v[148:149], v[20:21] op_sel_hi:[0,1,1]
	v_pk_fma_f32 v[22:23], v[122:123], v[150:151], v[22:23] op_sel_hi:[0,1,1]
	v_pk_fma_f32 v[24:25], v[122:123], v[152:153], v[24:25] op_sel_hi:[0,1,1]
	v_pk_fma_f32 v[26:27], v[122:123], v[154:155], v[26:27] op_sel_hi:[0,1,1]
	v_pk_fma_f32 v[28:29], v[122:123], v[156:157], v[28:29] op_sel_hi:[0,1,1]
	v_pk_fma_f32 v[30:31], v[122:123], v[158:159], v[30:31] op_sel_hi:[0,1,1]
	v_fmac_f32_e32 v2, v122, v192
	v_lshl_add_u64 v[32:33], v[32:33], 0, s[6:7]
	global_load_dword v122, v[32:33], off
	ds_read_b128 v[144:147], v5 offset:1920
	ds_read_b128 v[148:151], v5 offset:1936
	ds_read_b128 v[152:155], v5 offset:1952
	ds_read_b128 v[156:159], v5 offset:1968
	ds_read_b32 v192, v5 offset:1984
	s_waitcnt vmcnt(31) lgkmcnt(10)
	v_pk_fma_f32 v[16:17], v[124:125], v[160:161], v[16:17] op_sel_hi:[0,1,1]
	v_pk_fma_f32 v[18:19], v[124:125], v[162:163], v[18:19] op_sel_hi:[0,1,1]
	v_pk_fma_f32 v[20:21], v[124:125], v[164:165], v[20:21] op_sel_hi:[0,1,1]
	v_pk_fma_f32 v[22:23], v[124:125], v[166:167], v[22:23] op_sel_hi:[0,1,1]
	v_pk_fma_f32 v[24:25], v[124:125], v[168:169], v[24:25] op_sel_hi:[0,1,1]
	v_pk_fma_f32 v[26:27], v[124:125], v[170:171], v[26:27] op_sel_hi:[0,1,1]
	v_pk_fma_f32 v[28:29], v[124:125], v[172:173], v[28:29] op_sel_hi:[0,1,1]
	v_pk_fma_f32 v[30:31], v[124:125], v[174:175], v[30:31] op_sel_hi:[0,1,1]
	v_fmac_f32_e32 v2, v124, v193
	v_lshl_add_u64 v[32:33], v[32:33], 0, s[6:7]
	global_load_dword v124, v[32:33], off
	ds_read_b128 v[160:163], v5 offset:2000
	ds_read_b128 v[164:167], v5 offset:2016
	ds_read_b128 v[168:171], v5 offset:2032
	ds_read_b128 v[172:175], v5 offset:2048
	ds_read_b32 v193, v5 offset:2064
	s_waitcnt vmcnt(31) lgkmcnt(10)
	v_pk_fma_f32 v[16:17], v[126:127], v[176:177], v[16:17] op_sel_hi:[0,1,1]
	v_pk_fma_f32 v[18:19], v[126:127], v[178:179], v[18:19] op_sel_hi:[0,1,1]
	v_pk_fma_f32 v[20:21], v[126:127], v[180:181], v[20:21] op_sel_hi:[0,1,1]
	v_pk_fma_f32 v[22:23], v[126:127], v[182:183], v[22:23] op_sel_hi:[0,1,1]
	v_pk_fma_f32 v[24:25], v[126:127], v[184:185], v[24:25] op_sel_hi:[0,1,1]
	v_pk_fma_f32 v[26:27], v[126:127], v[186:187], v[26:27] op_sel_hi:[0,1,1]
	v_pk_fma_f32 v[28:29], v[126:127], v[188:189], v[28:29] op_sel_hi:[0,1,1]
	v_pk_fma_f32 v[30:31], v[126:127], v[190:191], v[30:31] op_sel_hi:[0,1,1]
	v_fmac_f32_e32 v2, v126, v194
	v_lshl_add_u64 v[32:33], v[32:33], 0, s[6:7]
	global_load_dword v126, v[32:33], off
	ds_read_b128 v[176:179], v5 offset:2080
	ds_read_b128 v[180:183], v5 offset:2096
	ds_read_b128 v[184:187], v5 offset:2112
	ds_read_b128 v[188:191], v5 offset:2128
	ds_read_b32 v194, v5 offset:2144
	s_waitcnt vmcnt(31) lgkmcnt(10)
	v_pk_fma_f32 v[16:17], v[128:129], v[144:145], v[16:17] op_sel_hi:[0,1,1]
	v_pk_fma_f32 v[18:19], v[128:129], v[146:147], v[18:19] op_sel_hi:[0,1,1]
	v_pk_fma_f32 v[20:21], v[128:129], v[148:149], v[20:21] op_sel_hi:[0,1,1]
	v_pk_fma_f32 v[22:23], v[128:129], v[150:151], v[22:23] op_sel_hi:[0,1,1]
	v_pk_fma_f32 v[24:25], v[128:129], v[152:153], v[24:25] op_sel_hi:[0,1,1]
	v_pk_fma_f32 v[26:27], v[128:129], v[154:155], v[26:27] op_sel_hi:[0,1,1]
	v_pk_fma_f32 v[28:29], v[128:129], v[156:157], v[28:29] op_sel_hi:[0,1,1]
	v_pk_fma_f32 v[30:31], v[128:129], v[158:159], v[30:31] op_sel_hi:[0,1,1]
	v_fmac_f32_e32 v2, v128, v192
	v_lshl_add_u64 v[32:33], v[32:33], 0, s[6:7]
	global_load_dword v128, v[32:33], off
	ds_read_b128 v[144:147], v5 offset:2160
	ds_read_b128 v[148:151], v5 offset:2176
	ds_read_b128 v[152:155], v5 offset:2192
	ds_read_b128 v[156:159], v5 offset:2208
	ds_read_b32 v192, v5 offset:2224
	s_waitcnt vmcnt(31) lgkmcnt(10)
	v_pk_fma_f32 v[16:17], v[130:131], v[160:161], v[16:17] op_sel_hi:[0,1,1]
	v_pk_fma_f32 v[18:19], v[130:131], v[162:163], v[18:19] op_sel_hi:[0,1,1]
	v_pk_fma_f32 v[20:21], v[130:131], v[164:165], v[20:21] op_sel_hi:[0,1,1]
	v_pk_fma_f32 v[22:23], v[130:131], v[166:167], v[22:23] op_sel_hi:[0,1,1]
	v_pk_fma_f32 v[24:25], v[130:131], v[168:169], v[24:25] op_sel_hi:[0,1,1]
	v_pk_fma_f32 v[26:27], v[130:131], v[170:171], v[26:27] op_sel_hi:[0,1,1]
	v_pk_fma_f32 v[28:29], v[130:131], v[172:173], v[28:29] op_sel_hi:[0,1,1]
	v_pk_fma_f32 v[30:31], v[130:131], v[174:175], v[30:31] op_sel_hi:[0,1,1]
	v_fmac_f32_e32 v2, v130, v193
	v_lshl_add_u64 v[32:33], v[32:33], 0, s[6:7]
	global_load_dword v130, v[32:33], off
	ds_read_b128 v[160:163], v5 offset:2240
	ds_read_b128 v[164:167], v5 offset:2256
	ds_read_b128 v[168:171], v5 offset:2272
	ds_read_b128 v[172:175], v5 offset:2288
	ds_read_b32 v193, v5 offset:2304
	s_waitcnt vmcnt(31) lgkmcnt(10)
	v_pk_fma_f32 v[16:17], v[132:133], v[176:177], v[16:17] op_sel_hi:[0,1,1]
	v_pk_fma_f32 v[18:19], v[132:133], v[178:179], v[18:19] op_sel_hi:[0,1,1]
	v_pk_fma_f32 v[20:21], v[132:133], v[180:181], v[20:21] op_sel_hi:[0,1,1]
	v_pk_fma_f32 v[22:23], v[132:133], v[182:183], v[22:23] op_sel_hi:[0,1,1]
	v_pk_fma_f32 v[24:25], v[132:133], v[184:185], v[24:25] op_sel_hi:[0,1,1]
	v_pk_fma_f32 v[26:27], v[132:133], v[186:187], v[26:27] op_sel_hi:[0,1,1]
	v_pk_fma_f32 v[28:29], v[132:133], v[188:189], v[28:29] op_sel_hi:[0,1,1]
	v_pk_fma_f32 v[30:31], v[132:133], v[190:191], v[30:31] op_sel_hi:[0,1,1]
	v_fmac_f32_e32 v2, v132, v194
	v_lshl_add_u64 v[32:33], v[32:33], 0, s[6:7]
	global_load_dword v132, v[32:33], off
	ds_read_b128 v[176:179], v5 offset:2320
	ds_read_b128 v[180:183], v5 offset:2336
	ds_read_b128 v[184:187], v5 offset:2352
	ds_read_b128 v[188:191], v5 offset:2368
	ds_read_b32 v194, v5 offset:2384
	s_waitcnt vmcnt(31) lgkmcnt(10)
	v_pk_fma_f32 v[16:17], v[134:135], v[144:145], v[16:17] op_sel_hi:[0,1,1]
	v_pk_fma_f32 v[18:19], v[134:135], v[146:147], v[18:19] op_sel_hi:[0,1,1]
	v_pk_fma_f32 v[20:21], v[134:135], v[148:149], v[20:21] op_sel_hi:[0,1,1]
	v_pk_fma_f32 v[22:23], v[134:135], v[150:151], v[22:23] op_sel_hi:[0,1,1]
	v_pk_fma_f32 v[24:25], v[134:135], v[152:153], v[24:25] op_sel_hi:[0,1,1]
	v_pk_fma_f32 v[26:27], v[134:135], v[154:155], v[26:27] op_sel_hi:[0,1,1]
	v_pk_fma_f32 v[28:29], v[134:135], v[156:157], v[28:29] op_sel_hi:[0,1,1]
	v_pk_fma_f32 v[30:31], v[134:135], v[158:159], v[30:31] op_sel_hi:[0,1,1]
	v_fmac_f32_e32 v2, v134, v192
	v_lshl_add_u64 v[32:33], v[32:33], 0, s[6:7]
	global_load_dword v134, v[32:33], off
	ds_read_b128 v[144:147], v5 offset:2400
	ds_read_b128 v[148:151], v5 offset:2416
	ds_read_b128 v[152:155], v5 offset:2432
	ds_read_b128 v[156:159], v5 offset:2448
	ds_read_b32 v192, v5 offset:2464
	s_waitcnt vmcnt(31) lgkmcnt(10)
	v_pk_fma_f32 v[16:17], v[136:137], v[160:161], v[16:17] op_sel_hi:[0,1,1]
	v_pk_fma_f32 v[18:19], v[136:137], v[162:163], v[18:19] op_sel_hi:[0,1,1]
	v_pk_fma_f32 v[20:21], v[136:137], v[164:165], v[20:21] op_sel_hi:[0,1,1]
	v_pk_fma_f32 v[22:23], v[136:137], v[166:167], v[22:23] op_sel_hi:[0,1,1]
	v_pk_fma_f32 v[24:25], v[136:137], v[168:169], v[24:25] op_sel_hi:[0,1,1]
	v_pk_fma_f32 v[26:27], v[136:137], v[170:171], v[26:27] op_sel_hi:[0,1,1]
	v_pk_fma_f32 v[28:29], v[136:137], v[172:173], v[28:29] op_sel_hi:[0,1,1]
	v_pk_fma_f32 v[30:31], v[136:137], v[174:175], v[30:31] op_sel_hi:[0,1,1]
	v_fmac_f32_e32 v2, v136, v193
	v_lshl_add_u64 v[32:33], v[32:33], 0, s[6:7]
	global_load_dword v136, v[32:33], off
	ds_read_b128 v[160:163], v5 offset:2480
	ds_read_b128 v[164:167], v5 offset:2496
	ds_read_b128 v[168:171], v5 offset:2512
	ds_read_b128 v[172:175], v5 offset:2528
	ds_read_b32 v193, v5 offset:2544
	s_waitcnt vmcnt(31) lgkmcnt(10)
	v_pk_fma_f32 v[16:17], v[138:139], v[176:177], v[16:17] op_sel_hi:[0,1,1]
	v_pk_fma_f32 v[18:19], v[138:139], v[178:179], v[18:19] op_sel_hi:[0,1,1]
	v_pk_fma_f32 v[20:21], v[138:139], v[180:181], v[20:21] op_sel_hi:[0,1,1]
	v_pk_fma_f32 v[22:23], v[138:139], v[182:183], v[22:23] op_sel_hi:[0,1,1]
	v_pk_fma_f32 v[24:25], v[138:139], v[184:185], v[24:25] op_sel_hi:[0,1,1]
	v_pk_fma_f32 v[26:27], v[138:139], v[186:187], v[26:27] op_sel_hi:[0,1,1]
	v_pk_fma_f32 v[28:29], v[138:139], v[188:189], v[28:29] op_sel_hi:[0,1,1]
	v_pk_fma_f32 v[30:31], v[138:139], v[190:191], v[30:31] op_sel_hi:[0,1,1]
	v_fmac_f32_e32 v2, v138, v194
	v_lshl_add_u64 v[32:33], v[32:33], 0, s[6:7]
	global_load_dword v138, v[32:33], off
	ds_read_b128 v[176:179], v5 offset:2560
	ds_read_b128 v[180:183], v5 offset:2576
	ds_read_b128 v[184:187], v5 offset:2592
	ds_read_b128 v[188:191], v5 offset:2608
	ds_read_b32 v194, v5 offset:2624
	s_waitcnt vmcnt(31) lgkmcnt(10)
	v_pk_fma_f32 v[16:17], v[140:141], v[144:145], v[16:17] op_sel_hi:[0,1,1]
	v_pk_fma_f32 v[18:19], v[140:141], v[146:147], v[18:19] op_sel_hi:[0,1,1]
	v_pk_fma_f32 v[20:21], v[140:141], v[148:149], v[20:21] op_sel_hi:[0,1,1]
	v_pk_fma_f32 v[22:23], v[140:141], v[150:151], v[22:23] op_sel_hi:[0,1,1]
	v_pk_fma_f32 v[24:25], v[140:141], v[152:153], v[24:25] op_sel_hi:[0,1,1]
	v_pk_fma_f32 v[26:27], v[140:141], v[154:155], v[26:27] op_sel_hi:[0,1,1]
	v_pk_fma_f32 v[28:29], v[140:141], v[156:157], v[28:29] op_sel_hi:[0,1,1]
	v_pk_fma_f32 v[30:31], v[140:141], v[158:159], v[30:31] op_sel_hi:[0,1,1]
	v_fmac_f32_e32 v2, v140, v192
	v_lshl_add_u64 v[32:33], v[32:33], 0, s[6:7]
	global_load_dword v140, v[32:33], off
	ds_read_b128 v[144:147], v5 offset:2640
	ds_read_b128 v[148:151], v5 offset:2656
	ds_read_b128 v[152:155], v5 offset:2672
	ds_read_b128 v[156:159], v5 offset:2688
	ds_read_b32 v192, v5 offset:2704
	s_waitcnt vmcnt(31) lgkmcnt(10)
	v_pk_fma_f32 v[16:17], v[142:143], v[160:161], v[16:17] op_sel_hi:[0,1,1]
	v_pk_fma_f32 v[18:19], v[142:143], v[162:163], v[18:19] op_sel_hi:[0,1,1]
	v_pk_fma_f32 v[20:21], v[142:143], v[164:165], v[20:21] op_sel_hi:[0,1,1]
	v_pk_fma_f32 v[22:23], v[142:143], v[166:167], v[22:23] op_sel_hi:[0,1,1]
	v_pk_fma_f32 v[24:25], v[142:143], v[168:169], v[24:25] op_sel_hi:[0,1,1]
	v_pk_fma_f32 v[26:27], v[142:143], v[170:171], v[26:27] op_sel_hi:[0,1,1]
	v_pk_fma_f32 v[28:29], v[142:143], v[172:173], v[28:29] op_sel_hi:[0,1,1]
	v_pk_fma_f32 v[30:31], v[142:143], v[174:175], v[30:31] op_sel_hi:[0,1,1]
	v_fmac_f32_e32 v2, v142, v193
	v_lshl_add_u64 v[32:33], v[32:33], 0, s[6:7]
	global_load_dword v142, v[32:33], off
	ds_read_b128 v[160:163], v5 offset:2720
	ds_read_b128 v[164:167], v5 offset:2736
	ds_read_b128 v[168:171], v5 offset:2752
	ds_read_b128 v[172:175], v5 offset:2768
	ds_read_b32 v193, v5 offset:2784
	s_waitcnt vmcnt(31) lgkmcnt(10)
	v_pk_fma_f32 v[16:17], v[80:81], v[176:177], v[16:17] op_sel_hi:[0,1,1]
	v_pk_fma_f32 v[18:19], v[80:81], v[178:179], v[18:19] op_sel_hi:[0,1,1]
	v_pk_fma_f32 v[20:21], v[80:81], v[180:181], v[20:21] op_sel_hi:[0,1,1]
	v_pk_fma_f32 v[22:23], v[80:81], v[182:183], v[22:23] op_sel_hi:[0,1,1]
	v_pk_fma_f32 v[24:25], v[80:81], v[184:185], v[24:25] op_sel_hi:[0,1,1]
	v_pk_fma_f32 v[26:27], v[80:81], v[186:187], v[26:27] op_sel_hi:[0,1,1]
	v_pk_fma_f32 v[28:29], v[80:81], v[188:189], v[28:29] op_sel_hi:[0,1,1]
	v_pk_fma_f32 v[30:31], v[80:81], v[190:191], v[30:31] op_sel_hi:[0,1,1]
	v_fmac_f32_e32 v2, v80, v194
	v_lshl_add_u64 v[32:33], v[32:33], 0, s[6:7]
	global_load_dword v80, v[32:33], off
	ds_read_b128 v[176:179], v5 offset:2800
	ds_read_b128 v[180:183], v5 offset:2816
	ds_read_b128 v[184:187], v5 offset:2832
	ds_read_b128 v[188:191], v5 offset:2848
	ds_read_b32 v194, v5 offset:2864
	s_waitcnt vmcnt(31) lgkmcnt(10)
	v_pk_fma_f32 v[16:17], v[82:83], v[144:145], v[16:17] op_sel_hi:[0,1,1]
	v_pk_fma_f32 v[18:19], v[82:83], v[146:147], v[18:19] op_sel_hi:[0,1,1]
	v_pk_fma_f32 v[20:21], v[82:83], v[148:149], v[20:21] op_sel_hi:[0,1,1]
	v_pk_fma_f32 v[22:23], v[82:83], v[150:151], v[22:23] op_sel_hi:[0,1,1]
	v_pk_fma_f32 v[24:25], v[82:83], v[152:153], v[24:25] op_sel_hi:[0,1,1]
	v_pk_fma_f32 v[26:27], v[82:83], v[154:155], v[26:27] op_sel_hi:[0,1,1]
	v_pk_fma_f32 v[28:29], v[82:83], v[156:157], v[28:29] op_sel_hi:[0,1,1]
	v_pk_fma_f32 v[30:31], v[82:83], v[158:159], v[30:31] op_sel_hi:[0,1,1]
	v_fmac_f32_e32 v2, v82, v192
	v_lshl_add_u64 v[32:33], v[32:33], 0, s[6:7]
	global_load_dword v82, v[32:33], off
	ds_read_b128 v[144:147], v5 offset:2880
	ds_read_b128 v[148:151], v5 offset:2896
	ds_read_b128 v[152:155], v5 offset:2912
	ds_read_b128 v[156:159], v5 offset:2928
	ds_read_b32 v192, v5 offset:2944
	s_waitcnt vmcnt(31) lgkmcnt(10)
	v_pk_fma_f32 v[16:17], v[84:85], v[160:161], v[16:17] op_sel_hi:[0,1,1]
	v_pk_fma_f32 v[18:19], v[84:85], v[162:163], v[18:19] op_sel_hi:[0,1,1]
	v_pk_fma_f32 v[20:21], v[84:85], v[164:165], v[20:21] op_sel_hi:[0,1,1]
	v_pk_fma_f32 v[22:23], v[84:85], v[166:167], v[22:23] op_sel_hi:[0,1,1]
	v_pk_fma_f32 v[24:25], v[84:85], v[168:169], v[24:25] op_sel_hi:[0,1,1]
	v_pk_fma_f32 v[26:27], v[84:85], v[170:171], v[26:27] op_sel_hi:[0,1,1]
	v_pk_fma_f32 v[28:29], v[84:85], v[172:173], v[28:29] op_sel_hi:[0,1,1]
	v_pk_fma_f32 v[30:31], v[84:85], v[174:175], v[30:31] op_sel_hi:[0,1,1]
	v_fmac_f32_e32 v2, v84, v193
	v_lshl_add_u64 v[32:33], v[32:33], 0, s[6:7]
	global_load_dword v84, v[32:33], off
	ds_read_b128 v[160:163], v5 offset:2960
	ds_read_b128 v[164:167], v5 offset:2976
	ds_read_b128 v[168:171], v5 offset:2992
	ds_read_b128 v[172:175], v5 offset:3008
	ds_read_b32 v193, v5 offset:3024
	s_waitcnt vmcnt(31) lgkmcnt(10)
	v_pk_fma_f32 v[16:17], v[86:87], v[176:177], v[16:17] op_sel_hi:[0,1,1]
	v_pk_fma_f32 v[18:19], v[86:87], v[178:179], v[18:19] op_sel_hi:[0,1,1]
	v_pk_fma_f32 v[20:21], v[86:87], v[180:181], v[20:21] op_sel_hi:[0,1,1]
	v_pk_fma_f32 v[22:23], v[86:87], v[182:183], v[22:23] op_sel_hi:[0,1,1]
	v_pk_fma_f32 v[24:25], v[86:87], v[184:185], v[24:25] op_sel_hi:[0,1,1]
	v_pk_fma_f32 v[26:27], v[86:87], v[186:187], v[26:27] op_sel_hi:[0,1,1]
	v_pk_fma_f32 v[28:29], v[86:87], v[188:189], v[28:29] op_sel_hi:[0,1,1]
	v_pk_fma_f32 v[30:31], v[86:87], v[190:191], v[30:31] op_sel_hi:[0,1,1]
	v_fmac_f32_e32 v2, v86, v194
	v_lshl_add_u64 v[32:33], v[32:33], 0, s[6:7]
	global_load_dword v86, v[32:33], off
	ds_read_b128 v[176:179], v5 offset:3040
	ds_read_b128 v[180:183], v5 offset:3056
	ds_read_b128 v[184:187], v5 offset:3072
	ds_read_b128 v[188:191], v5 offset:3088
	ds_read_b32 v194, v5 offset:3104
	s_waitcnt vmcnt(31) lgkmcnt(10)
	v_pk_fma_f32 v[16:17], v[88:89], v[144:145], v[16:17] op_sel_hi:[0,1,1]
	v_pk_fma_f32 v[18:19], v[88:89], v[146:147], v[18:19] op_sel_hi:[0,1,1]
	v_pk_fma_f32 v[20:21], v[88:89], v[148:149], v[20:21] op_sel_hi:[0,1,1]
	v_pk_fma_f32 v[22:23], v[88:89], v[150:151], v[22:23] op_sel_hi:[0,1,1]
	v_pk_fma_f32 v[24:25], v[88:89], v[152:153], v[24:25] op_sel_hi:[0,1,1]
	v_pk_fma_f32 v[26:27], v[88:89], v[154:155], v[26:27] op_sel_hi:[0,1,1]
	v_pk_fma_f32 v[28:29], v[88:89], v[156:157], v[28:29] op_sel_hi:[0,1,1]
	v_pk_fma_f32 v[30:31], v[88:89], v[158:159], v[30:31] op_sel_hi:[0,1,1]
	v_fmac_f32_e32 v2, v88, v192
	v_lshl_add_u64 v[32:33], v[32:33], 0, s[6:7]
	global_load_dword v88, v[32:33], off
	ds_read_b128 v[144:147], v5 offset:3120
	ds_read_b128 v[148:151], v5 offset:3136
	ds_read_b128 v[152:155], v5 offset:3152
	ds_read_b128 v[156:159], v5 offset:3168
	ds_read_b32 v192, v5 offset:3184
	s_waitcnt vmcnt(31) lgkmcnt(10)
	v_pk_fma_f32 v[16:17], v[90:91], v[160:161], v[16:17] op_sel_hi:[0,1,1]
	v_pk_fma_f32 v[18:19], v[90:91], v[162:163], v[18:19] op_sel_hi:[0,1,1]
	v_pk_fma_f32 v[20:21], v[90:91], v[164:165], v[20:21] op_sel_hi:[0,1,1]
	v_pk_fma_f32 v[22:23], v[90:91], v[166:167], v[22:23] op_sel_hi:[0,1,1]
	v_pk_fma_f32 v[24:25], v[90:91], v[168:169], v[24:25] op_sel_hi:[0,1,1]
	v_pk_fma_f32 v[26:27], v[90:91], v[170:171], v[26:27] op_sel_hi:[0,1,1]
	v_pk_fma_f32 v[28:29], v[90:91], v[172:173], v[28:29] op_sel_hi:[0,1,1]
	v_pk_fma_f32 v[30:31], v[90:91], v[174:175], v[30:31] op_sel_hi:[0,1,1]
	v_fmac_f32_e32 v2, v90, v193
	v_lshl_add_u64 v[32:33], v[32:33], 0, s[6:7]
	global_load_dword v90, v[32:33], off
	ds_read_b128 v[160:163], v5 offset:3200
	ds_read_b128 v[164:167], v5 offset:3216
	ds_read_b128 v[168:171], v5 offset:3232
	ds_read_b128 v[172:175], v5 offset:3248
	ds_read_b32 v193, v5 offset:3264
	s_waitcnt vmcnt(31) lgkmcnt(10)
	v_pk_fma_f32 v[16:17], v[92:93], v[176:177], v[16:17] op_sel_hi:[0,1,1]
	v_pk_fma_f32 v[18:19], v[92:93], v[178:179], v[18:19] op_sel_hi:[0,1,1]
	v_pk_fma_f32 v[20:21], v[92:93], v[180:181], v[20:21] op_sel_hi:[0,1,1]
	v_pk_fma_f32 v[22:23], v[92:93], v[182:183], v[22:23] op_sel_hi:[0,1,1]
	v_pk_fma_f32 v[24:25], v[92:93], v[184:185], v[24:25] op_sel_hi:[0,1,1]
	v_pk_fma_f32 v[26:27], v[92:93], v[186:187], v[26:27] op_sel_hi:[0,1,1]
	v_pk_fma_f32 v[28:29], v[92:93], v[188:189], v[28:29] op_sel_hi:[0,1,1]
	v_pk_fma_f32 v[30:31], v[92:93], v[190:191], v[30:31] op_sel_hi:[0,1,1]
	v_fmac_f32_e32 v2, v92, v194
	v_lshl_add_u64 v[32:33], v[32:33], 0, s[6:7]
	global_load_dword v92, v[32:33], off
	ds_read_b128 v[176:179], v5 offset:3280
	ds_read_b128 v[180:183], v5 offset:3296
	ds_read_b128 v[184:187], v5 offset:3312
	ds_read_b128 v[188:191], v5 offset:3328
	ds_read_b32 v194, v5 offset:3344
	s_waitcnt vmcnt(31) lgkmcnt(10)
	v_pk_fma_f32 v[16:17], v[94:95], v[144:145], v[16:17] op_sel_hi:[0,1,1]
	v_pk_fma_f32 v[18:19], v[94:95], v[146:147], v[18:19] op_sel_hi:[0,1,1]
	v_pk_fma_f32 v[20:21], v[94:95], v[148:149], v[20:21] op_sel_hi:[0,1,1]
	v_pk_fma_f32 v[22:23], v[94:95], v[150:151], v[22:23] op_sel_hi:[0,1,1]
	v_pk_fma_f32 v[24:25], v[94:95], v[152:153], v[24:25] op_sel_hi:[0,1,1]
	v_pk_fma_f32 v[26:27], v[94:95], v[154:155], v[26:27] op_sel_hi:[0,1,1]
	v_pk_fma_f32 v[28:29], v[94:95], v[156:157], v[28:29] op_sel_hi:[0,1,1]
	v_pk_fma_f32 v[30:31], v[94:95], v[158:159], v[30:31] op_sel_hi:[0,1,1]
	v_fmac_f32_e32 v2, v94, v192
	v_lshl_add_u64 v[32:33], v[32:33], 0, s[6:7]
	global_load_dword v94, v[32:33], off
	ds_read_b128 v[144:147], v5 offset:3360
	ds_read_b128 v[148:151], v5 offset:3376
	ds_read_b128 v[152:155], v5 offset:3392
	ds_read_b128 v[156:159], v5 offset:3408
	ds_read_b32 v192, v5 offset:3424
	s_waitcnt vmcnt(31) lgkmcnt(10)
	v_pk_fma_f32 v[16:17], v[96:97], v[160:161], v[16:17] op_sel_hi:[0,1,1]
	v_pk_fma_f32 v[18:19], v[96:97], v[162:163], v[18:19] op_sel_hi:[0,1,1]
	v_pk_fma_f32 v[20:21], v[96:97], v[164:165], v[20:21] op_sel_hi:[0,1,1]
	v_pk_fma_f32 v[22:23], v[96:97], v[166:167], v[22:23] op_sel_hi:[0,1,1]
	v_pk_fma_f32 v[24:25], v[96:97], v[168:169], v[24:25] op_sel_hi:[0,1,1]
	v_pk_fma_f32 v[26:27], v[96:97], v[170:171], v[26:27] op_sel_hi:[0,1,1]
	v_pk_fma_f32 v[28:29], v[96:97], v[172:173], v[28:29] op_sel_hi:[0,1,1]
	v_pk_fma_f32 v[30:31], v[96:97], v[174:175], v[30:31] op_sel_hi:[0,1,1]
	v_fmac_f32_e32 v2, v96, v193
	v_lshl_add_u64 v[32:33], v[32:33], 0, s[6:7]
	global_load_dword v96, v[32:33], off
	ds_read_b128 v[160:163], v5 offset:3440
	ds_read_b128 v[164:167], v5 offset:3456
	ds_read_b128 v[168:171], v5 offset:3472
	ds_read_b128 v[172:175], v5 offset:3488
	ds_read_b32 v193, v5 offset:3504
	s_waitcnt vmcnt(31) lgkmcnt(10)
	v_pk_fma_f32 v[16:17], v[98:99], v[176:177], v[16:17] op_sel_hi:[0,1,1]
	v_pk_fma_f32 v[18:19], v[98:99], v[178:179], v[18:19] op_sel_hi:[0,1,1]
	v_pk_fma_f32 v[20:21], v[98:99], v[180:181], v[20:21] op_sel_hi:[0,1,1]
	v_pk_fma_f32 v[22:23], v[98:99], v[182:183], v[22:23] op_sel_hi:[0,1,1]
	v_pk_fma_f32 v[24:25], v[98:99], v[184:185], v[24:25] op_sel_hi:[0,1,1]
	v_pk_fma_f32 v[26:27], v[98:99], v[186:187], v[26:27] op_sel_hi:[0,1,1]
	v_pk_fma_f32 v[28:29], v[98:99], v[188:189], v[28:29] op_sel_hi:[0,1,1]
	v_pk_fma_f32 v[30:31], v[98:99], v[190:191], v[30:31] op_sel_hi:[0,1,1]
	v_fmac_f32_e32 v2, v98, v194
	v_lshl_add_u64 v[32:33], v[32:33], 0, s[6:7]
	global_load_dword v98, v[32:33], off
	ds_read_b128 v[176:179], v5 offset:3520
	ds_read_b128 v[180:183], v5 offset:3536
	ds_read_b128 v[184:187], v5 offset:3552
	ds_read_b128 v[188:191], v5 offset:3568
	ds_read_b32 v194, v5 offset:3584
	s_waitcnt vmcnt(31) lgkmcnt(10)
	v_pk_fma_f32 v[16:17], v[100:101], v[144:145], v[16:17] op_sel_hi:[0,1,1]
	v_pk_fma_f32 v[18:19], v[100:101], v[146:147], v[18:19] op_sel_hi:[0,1,1]
	v_pk_fma_f32 v[20:21], v[100:101], v[148:149], v[20:21] op_sel_hi:[0,1,1]
	v_pk_fma_f32 v[22:23], v[100:101], v[150:151], v[22:23] op_sel_hi:[0,1,1]
	v_pk_fma_f32 v[24:25], v[100:101], v[152:153], v[24:25] op_sel_hi:[0,1,1]
	v_pk_fma_f32 v[26:27], v[100:101], v[154:155], v[26:27] op_sel_hi:[0,1,1]
	v_pk_fma_f32 v[28:29], v[100:101], v[156:157], v[28:29] op_sel_hi:[0,1,1]
	v_pk_fma_f32 v[30:31], v[100:101], v[158:159], v[30:31] op_sel_hi:[0,1,1]
	v_fmac_f32_e32 v2, v100, v192
	v_lshl_add_u64 v[32:33], v[32:33], 0, s[6:7]
	global_load_dword v100, v[32:33], off
	ds_read_b128 v[144:147], v5 offset:3600
	ds_read_b128 v[148:151], v5 offset:3616
	ds_read_b128 v[152:155], v5 offset:3632
	ds_read_b128 v[156:159], v5 offset:3648
	ds_read_b32 v192, v5 offset:3664
	s_waitcnt vmcnt(31) lgkmcnt(10)
	v_pk_fma_f32 v[16:17], v[102:103], v[160:161], v[16:17] op_sel_hi:[0,1,1]
	v_pk_fma_f32 v[18:19], v[102:103], v[162:163], v[18:19] op_sel_hi:[0,1,1]
	v_pk_fma_f32 v[20:21], v[102:103], v[164:165], v[20:21] op_sel_hi:[0,1,1]
	v_pk_fma_f32 v[22:23], v[102:103], v[166:167], v[22:23] op_sel_hi:[0,1,1]
	v_pk_fma_f32 v[24:25], v[102:103], v[168:169], v[24:25] op_sel_hi:[0,1,1]
	v_pk_fma_f32 v[26:27], v[102:103], v[170:171], v[26:27] op_sel_hi:[0,1,1]
	v_pk_fma_f32 v[28:29], v[102:103], v[172:173], v[28:29] op_sel_hi:[0,1,1]
	v_pk_fma_f32 v[30:31], v[102:103], v[174:175], v[30:31] op_sel_hi:[0,1,1]
	v_fmac_f32_e32 v2, v102, v193
	v_lshl_add_u64 v[32:33], v[32:33], 0, s[6:7]
	global_load_dword v102, v[32:33], off
	ds_read_b128 v[160:163], v5 offset:3680
	ds_read_b128 v[164:167], v5 offset:3696
	ds_read_b128 v[168:171], v5 offset:3712
	ds_read_b128 v[172:175], v5 offset:3728
	ds_read_b32 v193, v5 offset:3744
	s_waitcnt vmcnt(31) lgkmcnt(10)
	v_pk_fma_f32 v[16:17], v[104:105], v[176:177], v[16:17] op_sel_hi:[0,1,1]
	v_pk_fma_f32 v[18:19], v[104:105], v[178:179], v[18:19] op_sel_hi:[0,1,1]
	v_pk_fma_f32 v[20:21], v[104:105], v[180:181], v[20:21] op_sel_hi:[0,1,1]
	v_pk_fma_f32 v[22:23], v[104:105], v[182:183], v[22:23] op_sel_hi:[0,1,1]
	v_pk_fma_f32 v[24:25], v[104:105], v[184:185], v[24:25] op_sel_hi:[0,1,1]
	v_pk_fma_f32 v[26:27], v[104:105], v[186:187], v[26:27] op_sel_hi:[0,1,1]
	v_pk_fma_f32 v[28:29], v[104:105], v[188:189], v[28:29] op_sel_hi:[0,1,1]
	v_pk_fma_f32 v[30:31], v[104:105], v[190:191], v[30:31] op_sel_hi:[0,1,1]
	v_fmac_f32_e32 v2, v104, v194
	v_lshl_add_u64 v[32:33], v[32:33], 0, s[6:7]
	global_load_dword v104, v[32:33], off
	ds_read_b128 v[176:179], v5 offset:3760
	ds_read_b128 v[180:183], v5 offset:3776
	ds_read_b128 v[184:187], v5 offset:3792
	ds_read_b128 v[188:191], v5 offset:3808
	ds_read_b32 v194, v5 offset:3824
	s_waitcnt vmcnt(31) lgkmcnt(10)
	v_pk_fma_f32 v[16:17], v[106:107], v[144:145], v[16:17] op_sel_hi:[0,1,1]
	v_pk_fma_f32 v[18:19], v[106:107], v[146:147], v[18:19] op_sel_hi:[0,1,1]
	v_pk_fma_f32 v[20:21], v[106:107], v[148:149], v[20:21] op_sel_hi:[0,1,1]
	v_pk_fma_f32 v[22:23], v[106:107], v[150:151], v[22:23] op_sel_hi:[0,1,1]
	v_pk_fma_f32 v[24:25], v[106:107], v[152:153], v[24:25] op_sel_hi:[0,1,1]
	v_pk_fma_f32 v[26:27], v[106:107], v[154:155], v[26:27] op_sel_hi:[0,1,1]
	v_pk_fma_f32 v[28:29], v[106:107], v[156:157], v[28:29] op_sel_hi:[0,1,1]
	v_pk_fma_f32 v[30:31], v[106:107], v[158:159], v[30:31] op_sel_hi:[0,1,1]
	v_fmac_f32_e32 v2, v106, v192
	v_lshl_add_u64 v[32:33], v[32:33], 0, s[6:7]
	global_load_dword v106, v[32:33], off
	ds_read_b128 v[144:147], v5 offset:3840
	ds_read_b128 v[148:151], v5 offset:3856
	ds_read_b128 v[152:155], v5 offset:3872
	ds_read_b128 v[156:159], v5 offset:3888
	ds_read_b32 v192, v5 offset:3904
	s_waitcnt vmcnt(31) lgkmcnt(10)
	v_pk_fma_f32 v[16:17], v[108:109], v[160:161], v[16:17] op_sel_hi:[0,1,1]
	v_pk_fma_f32 v[18:19], v[108:109], v[162:163], v[18:19] op_sel_hi:[0,1,1]
	v_pk_fma_f32 v[20:21], v[108:109], v[164:165], v[20:21] op_sel_hi:[0,1,1]
	v_pk_fma_f32 v[22:23], v[108:109], v[166:167], v[22:23] op_sel_hi:[0,1,1]
	v_pk_fma_f32 v[24:25], v[108:109], v[168:169], v[24:25] op_sel_hi:[0,1,1]
	v_pk_fma_f32 v[26:27], v[108:109], v[170:171], v[26:27] op_sel_hi:[0,1,1]
	v_pk_fma_f32 v[28:29], v[108:109], v[172:173], v[28:29] op_sel_hi:[0,1,1]
	v_pk_fma_f32 v[30:31], v[108:109], v[174:175], v[30:31] op_sel_hi:[0,1,1]
	v_fmac_f32_e32 v2, v108, v193
	v_lshl_add_u64 v[32:33], v[32:33], 0, s[6:7]
	global_load_dword v108, v[32:33], off
	ds_read_b128 v[160:163], v5 offset:3920
	ds_read_b128 v[164:167], v5 offset:3936
	ds_read_b128 v[168:171], v5 offset:3952
	ds_read_b128 v[172:175], v5 offset:3968
	ds_read_b32 v193, v5 offset:3984
	s_waitcnt vmcnt(31) lgkmcnt(10)
	v_pk_fma_f32 v[16:17], v[110:111], v[176:177], v[16:17] op_sel_hi:[0,1,1]
	v_pk_fma_f32 v[18:19], v[110:111], v[178:179], v[18:19] op_sel_hi:[0,1,1]
	v_pk_fma_f32 v[20:21], v[110:111], v[180:181], v[20:21] op_sel_hi:[0,1,1]
	v_pk_fma_f32 v[22:23], v[110:111], v[182:183], v[22:23] op_sel_hi:[0,1,1]
	v_pk_fma_f32 v[24:25], v[110:111], v[184:185], v[24:25] op_sel_hi:[0,1,1]
	v_pk_fma_f32 v[26:27], v[110:111], v[186:187], v[26:27] op_sel_hi:[0,1,1]
	v_pk_fma_f32 v[28:29], v[110:111], v[188:189], v[28:29] op_sel_hi:[0,1,1]
	v_pk_fma_f32 v[30:31], v[110:111], v[190:191], v[30:31] op_sel_hi:[0,1,1]
	v_fmac_f32_e32 v2, v110, v194
	v_lshl_add_u64 v[32:33], v[32:33], 0, s[6:7]
	global_load_dword v110, v[32:33], off
	ds_read_b128 v[176:179], v5 offset:4000
	ds_read_b128 v[180:183], v5 offset:4016
	ds_read_b128 v[184:187], v5 offset:4032
	ds_read_b128 v[188:191], v5 offset:4048
	ds_read_b32 v194, v5 offset:4064
	s_waitcnt vmcnt(31) lgkmcnt(10)
	v_pk_fma_f32 v[16:17], v[112:113], v[144:145], v[16:17] op_sel_hi:[0,1,1]
	v_pk_fma_f32 v[18:19], v[112:113], v[146:147], v[18:19] op_sel_hi:[0,1,1]
	v_pk_fma_f32 v[20:21], v[112:113], v[148:149], v[20:21] op_sel_hi:[0,1,1]
	v_pk_fma_f32 v[22:23], v[112:113], v[150:151], v[22:23] op_sel_hi:[0,1,1]
	v_pk_fma_f32 v[24:25], v[112:113], v[152:153], v[24:25] op_sel_hi:[0,1,1]
	v_pk_fma_f32 v[26:27], v[112:113], v[154:155], v[26:27] op_sel_hi:[0,1,1]
	v_pk_fma_f32 v[28:29], v[112:113], v[156:157], v[28:29] op_sel_hi:[0,1,1]
	v_pk_fma_f32 v[30:31], v[112:113], v[158:159], v[30:31] op_sel_hi:[0,1,1]
	v_fmac_f32_e32 v2, v112, v192
	v_lshl_add_u64 v[32:33], v[32:33], 0, s[6:7]
	global_load_dword v112, v[32:33], off
	ds_read_b128 v[144:147], v5 offset:4080
	ds_read_b128 v[148:151], v5 offset:4096
	ds_read_b128 v[152:155], v5 offset:4112
	ds_read_b128 v[156:159], v5 offset:4128
	ds_read_b32 v192, v5 offset:4144
	s_waitcnt vmcnt(31) lgkmcnt(10)
	v_pk_fma_f32 v[16:17], v[114:115], v[160:161], v[16:17] op_sel_hi:[0,1,1]
	v_pk_fma_f32 v[18:19], v[114:115], v[162:163], v[18:19] op_sel_hi:[0,1,1]
	v_pk_fma_f32 v[20:21], v[114:115], v[164:165], v[20:21] op_sel_hi:[0,1,1]
	v_pk_fma_f32 v[22:23], v[114:115], v[166:167], v[22:23] op_sel_hi:[0,1,1]
	v_pk_fma_f32 v[24:25], v[114:115], v[168:169], v[24:25] op_sel_hi:[0,1,1]
	v_pk_fma_f32 v[26:27], v[114:115], v[170:171], v[26:27] op_sel_hi:[0,1,1]
	v_pk_fma_f32 v[28:29], v[114:115], v[172:173], v[28:29] op_sel_hi:[0,1,1]
	v_pk_fma_f32 v[30:31], v[114:115], v[174:175], v[30:31] op_sel_hi:[0,1,1]
	v_fmac_f32_e32 v2, v114, v193
	v_lshl_add_u64 v[32:33], v[32:33], 0, s[6:7]
	global_load_dword v114, v[32:33], off
	ds_read_b128 v[160:163], v5 offset:4160
	ds_read_b128 v[164:167], v5 offset:4176
	ds_read_b128 v[168:171], v5 offset:4192
	ds_read_b128 v[172:175], v5 offset:4208
	ds_read_b32 v193, v5 offset:4224
	s_waitcnt vmcnt(31) lgkmcnt(10)
	v_pk_fma_f32 v[16:17], v[116:117], v[176:177], v[16:17] op_sel_hi:[0,1,1]
	v_pk_fma_f32 v[18:19], v[116:117], v[178:179], v[18:19] op_sel_hi:[0,1,1]
	v_pk_fma_f32 v[20:21], v[116:117], v[180:181], v[20:21] op_sel_hi:[0,1,1]
	v_pk_fma_f32 v[22:23], v[116:117], v[182:183], v[22:23] op_sel_hi:[0,1,1]
	v_pk_fma_f32 v[24:25], v[116:117], v[184:185], v[24:25] op_sel_hi:[0,1,1]
	v_pk_fma_f32 v[26:27], v[116:117], v[186:187], v[26:27] op_sel_hi:[0,1,1]
	v_pk_fma_f32 v[28:29], v[116:117], v[188:189], v[28:29] op_sel_hi:[0,1,1]
	v_pk_fma_f32 v[30:31], v[116:117], v[190:191], v[30:31] op_sel_hi:[0,1,1]
	v_fmac_f32_e32 v2, v116, v194
	v_lshl_add_u64 v[32:33], v[32:33], 0, s[6:7]
	global_load_dword v116, v[32:33], off
	ds_read_b128 v[176:179], v5 offset:4240
	ds_read_b128 v[180:183], v5 offset:4256
	ds_read_b128 v[184:187], v5 offset:4272
	ds_read_b128 v[188:191], v5 offset:4288
	ds_read_b32 v194, v5 offset:4304
	s_waitcnt vmcnt(31) lgkmcnt(10)
	v_pk_fma_f32 v[16:17], v[118:119], v[144:145], v[16:17] op_sel_hi:[0,1,1]
	v_pk_fma_f32 v[18:19], v[118:119], v[146:147], v[18:19] op_sel_hi:[0,1,1]
	v_pk_fma_f32 v[20:21], v[118:119], v[148:149], v[20:21] op_sel_hi:[0,1,1]
	v_pk_fma_f32 v[22:23], v[118:119], v[150:151], v[22:23] op_sel_hi:[0,1,1]
	v_pk_fma_f32 v[24:25], v[118:119], v[152:153], v[24:25] op_sel_hi:[0,1,1]
	v_pk_fma_f32 v[26:27], v[118:119], v[154:155], v[26:27] op_sel_hi:[0,1,1]
	v_pk_fma_f32 v[28:29], v[118:119], v[156:157], v[28:29] op_sel_hi:[0,1,1]
	v_pk_fma_f32 v[30:31], v[118:119], v[158:159], v[30:31] op_sel_hi:[0,1,1]
	v_fmac_f32_e32 v2, v118, v192
	v_lshl_add_u64 v[32:33], v[32:33], 0, s[6:7]
	global_load_dword v118, v[32:33], off
	ds_read_b128 v[144:147], v5 offset:4320
	ds_read_b128 v[148:151], v5 offset:4336
	ds_read_b128 v[152:155], v5 offset:4352
	ds_read_b128 v[156:159], v5 offset:4368
	ds_read_b32 v192, v5 offset:4384
	s_waitcnt vmcnt(31) lgkmcnt(10)
	v_pk_fma_f32 v[16:17], v[120:121], v[160:161], v[16:17] op_sel_hi:[0,1,1]
	v_pk_fma_f32 v[18:19], v[120:121], v[162:163], v[18:19] op_sel_hi:[0,1,1]
	v_pk_fma_f32 v[20:21], v[120:121], v[164:165], v[20:21] op_sel_hi:[0,1,1]
	v_pk_fma_f32 v[22:23], v[120:121], v[166:167], v[22:23] op_sel_hi:[0,1,1]
	v_pk_fma_f32 v[24:25], v[120:121], v[168:169], v[24:25] op_sel_hi:[0,1,1]
	v_pk_fma_f32 v[26:27], v[120:121], v[170:171], v[26:27] op_sel_hi:[0,1,1]
	v_pk_fma_f32 v[28:29], v[120:121], v[172:173], v[28:29] op_sel_hi:[0,1,1]
	v_pk_fma_f32 v[30:31], v[120:121], v[174:175], v[30:31] op_sel_hi:[0,1,1]
	v_fmac_f32_e32 v2, v120, v193
	v_lshl_add_u64 v[32:33], v[32:33], 0, s[6:7]
	global_load_dword v120, v[32:33], off
	ds_read_b128 v[160:163], v5 offset:4400
	ds_read_b128 v[164:167], v5 offset:4416
	ds_read_b128 v[168:171], v5 offset:4432
	ds_read_b128 v[172:175], v5 offset:4448
	ds_read_b32 v193, v5 offset:4464
	s_waitcnt vmcnt(31) lgkmcnt(10)
	v_pk_fma_f32 v[16:17], v[122:123], v[176:177], v[16:17] op_sel_hi:[0,1,1]
	v_pk_fma_f32 v[18:19], v[122:123], v[178:179], v[18:19] op_sel_hi:[0,1,1]
	v_pk_fma_f32 v[20:21], v[122:123], v[180:181], v[20:21] op_sel_hi:[0,1,1]
	v_pk_fma_f32 v[22:23], v[122:123], v[182:183], v[22:23] op_sel_hi:[0,1,1]
	v_pk_fma_f32 v[24:25], v[122:123], v[184:185], v[24:25] op_sel_hi:[0,1,1]
	v_pk_fma_f32 v[26:27], v[122:123], v[186:187], v[26:27] op_sel_hi:[0,1,1]
	v_pk_fma_f32 v[28:29], v[122:123], v[188:189], v[28:29] op_sel_hi:[0,1,1]
	v_pk_fma_f32 v[30:31], v[122:123], v[190:191], v[30:31] op_sel_hi:[0,1,1]
	v_fmac_f32_e32 v2, v122, v194
	v_lshl_add_u64 v[32:33], v[32:33], 0, s[6:7]
	global_load_dword v122, v[32:33], off
	ds_read_b128 v[176:179], v5 offset:4480
	ds_read_b128 v[180:183], v5 offset:4496
	ds_read_b128 v[184:187], v5 offset:4512
	ds_read_b128 v[188:191], v5 offset:4528
	ds_read_b32 v194, v5 offset:4544
	s_waitcnt vmcnt(31) lgkmcnt(10)
	v_pk_fma_f32 v[16:17], v[124:125], v[144:145], v[16:17] op_sel_hi:[0,1,1]
	v_pk_fma_f32 v[18:19], v[124:125], v[146:147], v[18:19] op_sel_hi:[0,1,1]
	v_pk_fma_f32 v[20:21], v[124:125], v[148:149], v[20:21] op_sel_hi:[0,1,1]
	v_pk_fma_f32 v[22:23], v[124:125], v[150:151], v[22:23] op_sel_hi:[0,1,1]
	v_pk_fma_f32 v[24:25], v[124:125], v[152:153], v[24:25] op_sel_hi:[0,1,1]
	v_pk_fma_f32 v[26:27], v[124:125], v[154:155], v[26:27] op_sel_hi:[0,1,1]
	v_pk_fma_f32 v[28:29], v[124:125], v[156:157], v[28:29] op_sel_hi:[0,1,1]
	v_pk_fma_f32 v[30:31], v[124:125], v[158:159], v[30:31] op_sel_hi:[0,1,1]
	v_fmac_f32_e32 v2, v124, v192
	v_lshl_add_u64 v[32:33], v[32:33], 0, s[6:7]
	global_load_dword v124, v[32:33], off
	ds_read_b128 v[144:147], v5 offset:4560
	ds_read_b128 v[148:151], v5 offset:4576
	ds_read_b128 v[152:155], v5 offset:4592
	ds_read_b128 v[156:159], v5 offset:4608
	ds_read_b32 v192, v5 offset:4624
	s_waitcnt vmcnt(31) lgkmcnt(10)
	v_pk_fma_f32 v[16:17], v[126:127], v[160:161], v[16:17] op_sel_hi:[0,1,1]
	v_pk_fma_f32 v[18:19], v[126:127], v[162:163], v[18:19] op_sel_hi:[0,1,1]
	v_pk_fma_f32 v[20:21], v[126:127], v[164:165], v[20:21] op_sel_hi:[0,1,1]
	v_pk_fma_f32 v[22:23], v[126:127], v[166:167], v[22:23] op_sel_hi:[0,1,1]
	v_pk_fma_f32 v[24:25], v[126:127], v[168:169], v[24:25] op_sel_hi:[0,1,1]
	v_pk_fma_f32 v[26:27], v[126:127], v[170:171], v[26:27] op_sel_hi:[0,1,1]
	v_pk_fma_f32 v[28:29], v[126:127], v[172:173], v[28:29] op_sel_hi:[0,1,1]
	v_pk_fma_f32 v[30:31], v[126:127], v[174:175], v[30:31] op_sel_hi:[0,1,1]
	v_fmac_f32_e32 v2, v126, v193
	v_lshl_add_u64 v[32:33], v[32:33], 0, s[6:7]
	global_load_dword v126, v[32:33], off
	ds_read_b128 v[160:163], v5 offset:4640
	ds_read_b128 v[164:167], v5 offset:4656
	ds_read_b128 v[168:171], v5 offset:4672
	ds_read_b128 v[172:175], v5 offset:4688
	ds_read_b32 v193, v5 offset:4704
	s_waitcnt vmcnt(31) lgkmcnt(10)
	v_pk_fma_f32 v[16:17], v[128:129], v[176:177], v[16:17] op_sel_hi:[0,1,1]
	v_pk_fma_f32 v[18:19], v[128:129], v[178:179], v[18:19] op_sel_hi:[0,1,1]
	v_pk_fma_f32 v[20:21], v[128:129], v[180:181], v[20:21] op_sel_hi:[0,1,1]
	v_pk_fma_f32 v[22:23], v[128:129], v[182:183], v[22:23] op_sel_hi:[0,1,1]
	v_pk_fma_f32 v[24:25], v[128:129], v[184:185], v[24:25] op_sel_hi:[0,1,1]
	v_pk_fma_f32 v[26:27], v[128:129], v[186:187], v[26:27] op_sel_hi:[0,1,1]
	v_pk_fma_f32 v[28:29], v[128:129], v[188:189], v[28:29] op_sel_hi:[0,1,1]
	v_pk_fma_f32 v[30:31], v[128:129], v[190:191], v[30:31] op_sel_hi:[0,1,1]
	v_fmac_f32_e32 v2, v128, v194
	v_lshl_add_u64 v[32:33], v[32:33], 0, s[6:7]
	global_load_dword v128, v[32:33], off
	ds_read_b128 v[176:179], v5 offset:4720
	ds_read_b128 v[180:183], v5 offset:4736
	ds_read_b128 v[184:187], v5 offset:4752
	ds_read_b128 v[188:191], v5 offset:4768
	ds_read_b32 v194, v5 offset:4784
	s_waitcnt vmcnt(31) lgkmcnt(10)
	v_pk_fma_f32 v[16:17], v[130:131], v[144:145], v[16:17] op_sel_hi:[0,1,1]
	v_pk_fma_f32 v[18:19], v[130:131], v[146:147], v[18:19] op_sel_hi:[0,1,1]
	v_pk_fma_f32 v[20:21], v[130:131], v[148:149], v[20:21] op_sel_hi:[0,1,1]
	v_pk_fma_f32 v[22:23], v[130:131], v[150:151], v[22:23] op_sel_hi:[0,1,1]
	v_pk_fma_f32 v[24:25], v[130:131], v[152:153], v[24:25] op_sel_hi:[0,1,1]
	v_pk_fma_f32 v[26:27], v[130:131], v[154:155], v[26:27] op_sel_hi:[0,1,1]
	v_pk_fma_f32 v[28:29], v[130:131], v[156:157], v[28:29] op_sel_hi:[0,1,1]
	v_pk_fma_f32 v[30:31], v[130:131], v[158:159], v[30:31] op_sel_hi:[0,1,1]
	v_fmac_f32_e32 v2, v130, v192
	v_lshl_add_u64 v[32:33], v[32:33], 0, s[6:7]
	global_load_dword v130, v[32:33], off
	ds_read_b128 v[144:147], v5 offset:4800
	ds_read_b128 v[148:151], v5 offset:4816
	ds_read_b128 v[152:155], v5 offset:4832
	ds_read_b128 v[156:159], v5 offset:4848
	ds_read_b32 v192, v5 offset:4864
	s_waitcnt vmcnt(31) lgkmcnt(10)
	v_pk_fma_f32 v[16:17], v[132:133], v[160:161], v[16:17] op_sel_hi:[0,1,1]
	v_pk_fma_f32 v[18:19], v[132:133], v[162:163], v[18:19] op_sel_hi:[0,1,1]
	v_pk_fma_f32 v[20:21], v[132:133], v[164:165], v[20:21] op_sel_hi:[0,1,1]
	v_pk_fma_f32 v[22:23], v[132:133], v[166:167], v[22:23] op_sel_hi:[0,1,1]
	v_pk_fma_f32 v[24:25], v[132:133], v[168:169], v[24:25] op_sel_hi:[0,1,1]
	v_pk_fma_f32 v[26:27], v[132:133], v[170:171], v[26:27] op_sel_hi:[0,1,1]
	v_pk_fma_f32 v[28:29], v[132:133], v[172:173], v[28:29] op_sel_hi:[0,1,1]
	v_pk_fma_f32 v[30:31], v[132:133], v[174:175], v[30:31] op_sel_hi:[0,1,1]
	v_fmac_f32_e32 v2, v132, v193
	v_lshl_add_u64 v[32:33], v[32:33], 0, s[6:7]
	global_load_dword v132, v[32:33], off
	ds_read_b128 v[160:163], v5 offset:4880
	ds_read_b128 v[164:167], v5 offset:4896
	ds_read_b128 v[168:171], v5 offset:4912
	ds_read_b128 v[172:175], v5 offset:4928
	ds_read_b32 v193, v5 offset:4944
	s_waitcnt vmcnt(31) lgkmcnt(10)
	v_pk_fma_f32 v[16:17], v[134:135], v[176:177], v[16:17] op_sel_hi:[0,1,1]
	v_pk_fma_f32 v[18:19], v[134:135], v[178:179], v[18:19] op_sel_hi:[0,1,1]
	v_pk_fma_f32 v[20:21], v[134:135], v[180:181], v[20:21] op_sel_hi:[0,1,1]
	v_pk_fma_f32 v[22:23], v[134:135], v[182:183], v[22:23] op_sel_hi:[0,1,1]
	v_pk_fma_f32 v[24:25], v[134:135], v[184:185], v[24:25] op_sel_hi:[0,1,1]
	v_pk_fma_f32 v[26:27], v[134:135], v[186:187], v[26:27] op_sel_hi:[0,1,1]
	v_pk_fma_f32 v[28:29], v[134:135], v[188:189], v[28:29] op_sel_hi:[0,1,1]
	v_pk_fma_f32 v[30:31], v[134:135], v[190:191], v[30:31] op_sel_hi:[0,1,1]
	v_fmac_f32_e32 v2, v134, v194
	v_lshl_add_u64 v[32:33], v[32:33], 0, s[6:7]
	global_load_dword v134, v[32:33], off
	ds_read_b128 v[176:179], v5 offset:4960
	ds_read_b128 v[180:183], v5 offset:4976
	ds_read_b128 v[184:187], v5 offset:4992
	ds_read_b128 v[188:191], v5 offset:5008
	ds_read_b32 v194, v5 offset:5024
	s_waitcnt vmcnt(31) lgkmcnt(10)
	v_pk_fma_f32 v[16:17], v[136:137], v[144:145], v[16:17] op_sel_hi:[0,1,1]
	v_pk_fma_f32 v[18:19], v[136:137], v[146:147], v[18:19] op_sel_hi:[0,1,1]
	v_pk_fma_f32 v[20:21], v[136:137], v[148:149], v[20:21] op_sel_hi:[0,1,1]
	v_pk_fma_f32 v[22:23], v[136:137], v[150:151], v[22:23] op_sel_hi:[0,1,1]
	v_pk_fma_f32 v[24:25], v[136:137], v[152:153], v[24:25] op_sel_hi:[0,1,1]
	v_pk_fma_f32 v[26:27], v[136:137], v[154:155], v[26:27] op_sel_hi:[0,1,1]
	v_pk_fma_f32 v[28:29], v[136:137], v[156:157], v[28:29] op_sel_hi:[0,1,1]
	v_pk_fma_f32 v[30:31], v[136:137], v[158:159], v[30:31] op_sel_hi:[0,1,1]
	v_fmac_f32_e32 v2, v136, v192
	v_lshl_add_u64 v[32:33], v[32:33], 0, s[6:7]
	global_load_dword v136, v[32:33], off
	ds_read_b128 v[144:147], v5 offset:5040
	ds_read_b128 v[148:151], v5 offset:5056
	ds_read_b128 v[152:155], v5 offset:5072
	ds_read_b128 v[156:159], v5 offset:5088
	ds_read_b32 v192, v5 offset:5104
	s_waitcnt vmcnt(31) lgkmcnt(10)
	v_pk_fma_f32 v[16:17], v[138:139], v[160:161], v[16:17] op_sel_hi:[0,1,1]
	v_pk_fma_f32 v[18:19], v[138:139], v[162:163], v[18:19] op_sel_hi:[0,1,1]
	v_pk_fma_f32 v[20:21], v[138:139], v[164:165], v[20:21] op_sel_hi:[0,1,1]
	v_pk_fma_f32 v[22:23], v[138:139], v[166:167], v[22:23] op_sel_hi:[0,1,1]
	v_pk_fma_f32 v[24:25], v[138:139], v[168:169], v[24:25] op_sel_hi:[0,1,1]
	v_pk_fma_f32 v[26:27], v[138:139], v[170:171], v[26:27] op_sel_hi:[0,1,1]
	v_pk_fma_f32 v[28:29], v[138:139], v[172:173], v[28:29] op_sel_hi:[0,1,1]
	v_pk_fma_f32 v[30:31], v[138:139], v[174:175], v[30:31] op_sel_hi:[0,1,1]
	v_fmac_f32_e32 v2, v138, v193
	v_lshl_add_u64 v[32:33], v[32:33], 0, s[6:7]
	global_load_dword v138, v[32:33], off
	ds_read_b128 v[160:163], v5 offset:5120
	ds_read_b128 v[164:167], v5 offset:5136
	ds_read_b128 v[168:171], v5 offset:5152
	ds_read_b128 v[172:175], v5 offset:5168
	ds_read_b32 v193, v5 offset:5184
	s_waitcnt vmcnt(31) lgkmcnt(10)
	v_pk_fma_f32 v[16:17], v[140:141], v[176:177], v[16:17] op_sel_hi:[0,1,1]
	v_pk_fma_f32 v[18:19], v[140:141], v[178:179], v[18:19] op_sel_hi:[0,1,1]
	v_pk_fma_f32 v[20:21], v[140:141], v[180:181], v[20:21] op_sel_hi:[0,1,1]
	v_pk_fma_f32 v[22:23], v[140:141], v[182:183], v[22:23] op_sel_hi:[0,1,1]
	v_pk_fma_f32 v[24:25], v[140:141], v[184:185], v[24:25] op_sel_hi:[0,1,1]
	v_pk_fma_f32 v[26:27], v[140:141], v[186:187], v[26:27] op_sel_hi:[0,1,1]
	v_pk_fma_f32 v[28:29], v[140:141], v[188:189], v[28:29] op_sel_hi:[0,1,1]
	v_pk_fma_f32 v[30:31], v[140:141], v[190:191], v[30:31] op_sel_hi:[0,1,1]
	v_fmac_f32_e32 v2, v140, v194
	v_lshl_add_u64 v[32:33], v[32:33], 0, s[6:7]
	global_load_dword v140, v[32:33], off
	ds_read_b128 v[176:179], v5 offset:5200
	ds_read_b128 v[180:183], v5 offset:5216
	ds_read_b128 v[184:187], v5 offset:5232
	ds_read_b128 v[188:191], v5 offset:5248
	ds_read_b32 v194, v5 offset:5264
	s_waitcnt vmcnt(31) lgkmcnt(10)
	v_pk_fma_f32 v[16:17], v[142:143], v[144:145], v[16:17] op_sel_hi:[0,1,1]
	v_pk_fma_f32 v[18:19], v[142:143], v[146:147], v[18:19] op_sel_hi:[0,1,1]
	v_pk_fma_f32 v[20:21], v[142:143], v[148:149], v[20:21] op_sel_hi:[0,1,1]
	v_pk_fma_f32 v[22:23], v[142:143], v[150:151], v[22:23] op_sel_hi:[0,1,1]
	v_pk_fma_f32 v[24:25], v[142:143], v[152:153], v[24:25] op_sel_hi:[0,1,1]
	v_pk_fma_f32 v[26:27], v[142:143], v[154:155], v[26:27] op_sel_hi:[0,1,1]
	v_pk_fma_f32 v[28:29], v[142:143], v[156:157], v[28:29] op_sel_hi:[0,1,1]
	v_pk_fma_f32 v[30:31], v[142:143], v[158:159], v[30:31] op_sel_hi:[0,1,1]
	v_fmac_f32_e32 v2, v142, v192
	v_lshl_add_u64 v[32:33], v[32:33], 0, s[6:7]
	global_load_dword v142, v[32:33], off
	ds_read_b128 v[144:147], v5 offset:5280
	ds_read_b128 v[148:151], v5 offset:5296
	ds_read_b128 v[152:155], v5 offset:5312
	ds_read_b128 v[156:159], v5 offset:5328
	ds_read_b32 v192, v5 offset:5344
	s_waitcnt vmcnt(31) lgkmcnt(10)
	v_pk_fma_f32 v[16:17], v[80:81], v[160:161], v[16:17] op_sel_hi:[0,1,1]
	v_pk_fma_f32 v[18:19], v[80:81], v[162:163], v[18:19] op_sel_hi:[0,1,1]
	v_pk_fma_f32 v[20:21], v[80:81], v[164:165], v[20:21] op_sel_hi:[0,1,1]
	v_pk_fma_f32 v[22:23], v[80:81], v[166:167], v[22:23] op_sel_hi:[0,1,1]
	v_pk_fma_f32 v[24:25], v[80:81], v[168:169], v[24:25] op_sel_hi:[0,1,1]
	v_pk_fma_f32 v[26:27], v[80:81], v[170:171], v[26:27] op_sel_hi:[0,1,1]
	v_pk_fma_f32 v[28:29], v[80:81], v[172:173], v[28:29] op_sel_hi:[0,1,1]
	v_pk_fma_f32 v[30:31], v[80:81], v[174:175], v[30:31] op_sel_hi:[0,1,1]
	v_fmac_f32_e32 v2, v80, v193
	v_lshl_add_u64 v[32:33], v[32:33], 0, s[6:7]
	global_load_dword v80, v[32:33], off
	ds_read_b128 v[160:163], v5 offset:5360
	ds_read_b128 v[164:167], v5 offset:5376
	ds_read_b128 v[168:171], v5 offset:5392
	ds_read_b128 v[172:175], v5 offset:5408
	ds_read_b32 v193, v5 offset:5424
	s_waitcnt vmcnt(31) lgkmcnt(10)
	v_pk_fma_f32 v[16:17], v[82:83], v[176:177], v[16:17] op_sel_hi:[0,1,1]
	v_pk_fma_f32 v[18:19], v[82:83], v[178:179], v[18:19] op_sel_hi:[0,1,1]
	v_pk_fma_f32 v[20:21], v[82:83], v[180:181], v[20:21] op_sel_hi:[0,1,1]
	v_pk_fma_f32 v[22:23], v[82:83], v[182:183], v[22:23] op_sel_hi:[0,1,1]
	v_pk_fma_f32 v[24:25], v[82:83], v[184:185], v[24:25] op_sel_hi:[0,1,1]
	v_pk_fma_f32 v[26:27], v[82:83], v[186:187], v[26:27] op_sel_hi:[0,1,1]
	v_pk_fma_f32 v[28:29], v[82:83], v[188:189], v[28:29] op_sel_hi:[0,1,1]
	v_pk_fma_f32 v[30:31], v[82:83], v[190:191], v[30:31] op_sel_hi:[0,1,1]
	v_fmac_f32_e32 v2, v82, v194
	v_lshl_add_u64 v[32:33], v[32:33], 0, s[6:7]
	global_load_dword v82, v[32:33], off
	ds_read_b128 v[176:179], v5 offset:5440
	ds_read_b128 v[180:183], v5 offset:5456
	ds_read_b128 v[184:187], v5 offset:5472
	ds_read_b128 v[188:191], v5 offset:5488
	ds_read_b32 v194, v5 offset:5504
	s_waitcnt vmcnt(31) lgkmcnt(10)
	v_pk_fma_f32 v[16:17], v[84:85], v[144:145], v[16:17] op_sel_hi:[0,1,1]
	v_pk_fma_f32 v[18:19], v[84:85], v[146:147], v[18:19] op_sel_hi:[0,1,1]
	v_pk_fma_f32 v[20:21], v[84:85], v[148:149], v[20:21] op_sel_hi:[0,1,1]
	v_pk_fma_f32 v[22:23], v[84:85], v[150:151], v[22:23] op_sel_hi:[0,1,1]
	v_pk_fma_f32 v[24:25], v[84:85], v[152:153], v[24:25] op_sel_hi:[0,1,1]
	v_pk_fma_f32 v[26:27], v[84:85], v[154:155], v[26:27] op_sel_hi:[0,1,1]
	v_pk_fma_f32 v[28:29], v[84:85], v[156:157], v[28:29] op_sel_hi:[0,1,1]
	v_pk_fma_f32 v[30:31], v[84:85], v[158:159], v[30:31] op_sel_hi:[0,1,1]
	v_fmac_f32_e32 v2, v84, v192
	v_lshl_add_u64 v[32:33], v[32:33], 0, s[6:7]
	global_load_dword v84, v[32:33], off
	ds_read_b128 v[144:147], v5 offset:5520
	ds_read_b128 v[148:151], v5 offset:5536
	ds_read_b128 v[152:155], v5 offset:5552
	ds_read_b128 v[156:159], v5 offset:5568
	ds_read_b32 v192, v5 offset:5584
	s_waitcnt vmcnt(31) lgkmcnt(10)
	v_pk_fma_f32 v[16:17], v[86:87], v[160:161], v[16:17] op_sel_hi:[0,1,1]
	v_pk_fma_f32 v[18:19], v[86:87], v[162:163], v[18:19] op_sel_hi:[0,1,1]
	v_pk_fma_f32 v[20:21], v[86:87], v[164:165], v[20:21] op_sel_hi:[0,1,1]
	v_pk_fma_f32 v[22:23], v[86:87], v[166:167], v[22:23] op_sel_hi:[0,1,1]
	v_pk_fma_f32 v[24:25], v[86:87], v[168:169], v[24:25] op_sel_hi:[0,1,1]
	v_pk_fma_f32 v[26:27], v[86:87], v[170:171], v[26:27] op_sel_hi:[0,1,1]
	v_pk_fma_f32 v[28:29], v[86:87], v[172:173], v[28:29] op_sel_hi:[0,1,1]
	v_pk_fma_f32 v[30:31], v[86:87], v[174:175], v[30:31] op_sel_hi:[0,1,1]
	v_fmac_f32_e32 v2, v86, v193
	v_lshl_add_u64 v[32:33], v[32:33], 0, s[6:7]
	global_load_dword v86, v[32:33], off
	ds_read_b128 v[160:163], v5 offset:5600
	ds_read_b128 v[164:167], v5 offset:5616
	ds_read_b128 v[168:171], v5 offset:5632
	ds_read_b128 v[172:175], v5 offset:5648
	ds_read_b32 v193, v5 offset:5664
	s_waitcnt vmcnt(31) lgkmcnt(10)
	v_pk_fma_f32 v[16:17], v[88:89], v[176:177], v[16:17] op_sel_hi:[0,1,1]
	v_pk_fma_f32 v[18:19], v[88:89], v[178:179], v[18:19] op_sel_hi:[0,1,1]
	v_pk_fma_f32 v[20:21], v[88:89], v[180:181], v[20:21] op_sel_hi:[0,1,1]
	v_pk_fma_f32 v[22:23], v[88:89], v[182:183], v[22:23] op_sel_hi:[0,1,1]
	v_pk_fma_f32 v[24:25], v[88:89], v[184:185], v[24:25] op_sel_hi:[0,1,1]
	v_pk_fma_f32 v[26:27], v[88:89], v[186:187], v[26:27] op_sel_hi:[0,1,1]
	v_pk_fma_f32 v[28:29], v[88:89], v[188:189], v[28:29] op_sel_hi:[0,1,1]
	v_pk_fma_f32 v[30:31], v[88:89], v[190:191], v[30:31] op_sel_hi:[0,1,1]
	v_fmac_f32_e32 v2, v88, v194
	v_lshl_add_u64 v[32:33], v[32:33], 0, s[6:7]
	global_load_dword v88, v[32:33], off
	ds_read_b128 v[176:179], v5 offset:5680
	ds_read_b128 v[180:183], v5 offset:5696
	ds_read_b128 v[184:187], v5 offset:5712
	ds_read_b128 v[188:191], v5 offset:5728
	ds_read_b32 v194, v5 offset:5744
	s_waitcnt vmcnt(31) lgkmcnt(10)
	v_pk_fma_f32 v[16:17], v[90:91], v[144:145], v[16:17] op_sel_hi:[0,1,1]
	v_pk_fma_f32 v[18:19], v[90:91], v[146:147], v[18:19] op_sel_hi:[0,1,1]
	v_pk_fma_f32 v[20:21], v[90:91], v[148:149], v[20:21] op_sel_hi:[0,1,1]
	v_pk_fma_f32 v[22:23], v[90:91], v[150:151], v[22:23] op_sel_hi:[0,1,1]
	v_pk_fma_f32 v[24:25], v[90:91], v[152:153], v[24:25] op_sel_hi:[0,1,1]
	v_pk_fma_f32 v[26:27], v[90:91], v[154:155], v[26:27] op_sel_hi:[0,1,1]
	v_pk_fma_f32 v[28:29], v[90:91], v[156:157], v[28:29] op_sel_hi:[0,1,1]
	v_pk_fma_f32 v[30:31], v[90:91], v[158:159], v[30:31] op_sel_hi:[0,1,1]
	v_fmac_f32_e32 v2, v90, v192
	v_lshl_add_u64 v[32:33], v[32:33], 0, s[6:7]
	global_load_dword v90, v[32:33], off
	ds_read_b128 v[144:147], v5 offset:5760
	ds_read_b128 v[148:151], v5 offset:5776
	ds_read_b128 v[152:155], v5 offset:5792
	ds_read_b128 v[156:159], v5 offset:5808
	ds_read_b32 v192, v5 offset:5824
	s_waitcnt vmcnt(31) lgkmcnt(10)
	v_pk_fma_f32 v[16:17], v[92:93], v[160:161], v[16:17] op_sel_hi:[0,1,1]
	v_pk_fma_f32 v[18:19], v[92:93], v[162:163], v[18:19] op_sel_hi:[0,1,1]
	v_pk_fma_f32 v[20:21], v[92:93], v[164:165], v[20:21] op_sel_hi:[0,1,1]
	v_pk_fma_f32 v[22:23], v[92:93], v[166:167], v[22:23] op_sel_hi:[0,1,1]
	v_pk_fma_f32 v[24:25], v[92:93], v[168:169], v[24:25] op_sel_hi:[0,1,1]
	v_pk_fma_f32 v[26:27], v[92:93], v[170:171], v[26:27] op_sel_hi:[0,1,1]
	v_pk_fma_f32 v[28:29], v[92:93], v[172:173], v[28:29] op_sel_hi:[0,1,1]
	v_pk_fma_f32 v[30:31], v[92:93], v[174:175], v[30:31] op_sel_hi:[0,1,1]
	v_fmac_f32_e32 v2, v92, v193
	v_lshl_add_u64 v[32:33], v[32:33], 0, s[6:7]
	global_load_dword v92, v[32:33], off
	ds_read_b128 v[160:163], v5 offset:5840
	ds_read_b128 v[164:167], v5 offset:5856
	ds_read_b128 v[168:171], v5 offset:5872
	ds_read_b128 v[172:175], v5 offset:5888
	ds_read_b32 v193, v5 offset:5904
	s_waitcnt vmcnt(31) lgkmcnt(10)
	v_pk_fma_f32 v[16:17], v[94:95], v[176:177], v[16:17] op_sel_hi:[0,1,1]
	v_pk_fma_f32 v[18:19], v[94:95], v[178:179], v[18:19] op_sel_hi:[0,1,1]
	v_pk_fma_f32 v[20:21], v[94:95], v[180:181], v[20:21] op_sel_hi:[0,1,1]
	v_pk_fma_f32 v[22:23], v[94:95], v[182:183], v[22:23] op_sel_hi:[0,1,1]
	v_pk_fma_f32 v[24:25], v[94:95], v[184:185], v[24:25] op_sel_hi:[0,1,1]
	v_pk_fma_f32 v[26:27], v[94:95], v[186:187], v[26:27] op_sel_hi:[0,1,1]
	v_pk_fma_f32 v[28:29], v[94:95], v[188:189], v[28:29] op_sel_hi:[0,1,1]
	v_pk_fma_f32 v[30:31], v[94:95], v[190:191], v[30:31] op_sel_hi:[0,1,1]
	v_fmac_f32_e32 v2, v94, v194
	v_lshl_add_u64 v[32:33], v[32:33], 0, s[6:7]
	global_load_dword v94, v[32:33], off
	ds_read_b128 v[176:179], v5 offset:5920
	ds_read_b128 v[180:183], v5 offset:5936
	ds_read_b128 v[184:187], v5 offset:5952
	ds_read_b128 v[188:191], v5 offset:5968
	ds_read_b32 v194, v5 offset:5984
	s_waitcnt vmcnt(31) lgkmcnt(10)
	v_pk_fma_f32 v[16:17], v[96:97], v[144:145], v[16:17] op_sel_hi:[0,1,1]
	v_pk_fma_f32 v[18:19], v[96:97], v[146:147], v[18:19] op_sel_hi:[0,1,1]
	v_pk_fma_f32 v[20:21], v[96:97], v[148:149], v[20:21] op_sel_hi:[0,1,1]
	v_pk_fma_f32 v[22:23], v[96:97], v[150:151], v[22:23] op_sel_hi:[0,1,1]
	v_pk_fma_f32 v[24:25], v[96:97], v[152:153], v[24:25] op_sel_hi:[0,1,1]
	v_pk_fma_f32 v[26:27], v[96:97], v[154:155], v[26:27] op_sel_hi:[0,1,1]
	v_pk_fma_f32 v[28:29], v[96:97], v[156:157], v[28:29] op_sel_hi:[0,1,1]
	v_pk_fma_f32 v[30:31], v[96:97], v[158:159], v[30:31] op_sel_hi:[0,1,1]
	v_fmac_f32_e32 v2, v96, v192
	v_lshl_add_u64 v[32:33], v[32:33], 0, s[6:7]
	global_load_dword v96, v[32:33], off
	ds_read_b128 v[144:147], v5 offset:6000
	ds_read_b128 v[148:151], v5 offset:6016
	ds_read_b128 v[152:155], v5 offset:6032
	ds_read_b128 v[156:159], v5 offset:6048
	ds_read_b32 v192, v5 offset:6064
	s_waitcnt vmcnt(31) lgkmcnt(10)
	v_pk_fma_f32 v[16:17], v[98:99], v[160:161], v[16:17] op_sel_hi:[0,1,1]
	v_pk_fma_f32 v[18:19], v[98:99], v[162:163], v[18:19] op_sel_hi:[0,1,1]
	v_pk_fma_f32 v[20:21], v[98:99], v[164:165], v[20:21] op_sel_hi:[0,1,1]
	v_pk_fma_f32 v[22:23], v[98:99], v[166:167], v[22:23] op_sel_hi:[0,1,1]
	v_pk_fma_f32 v[24:25], v[98:99], v[168:169], v[24:25] op_sel_hi:[0,1,1]
	v_pk_fma_f32 v[26:27], v[98:99], v[170:171], v[26:27] op_sel_hi:[0,1,1]
	v_pk_fma_f32 v[28:29], v[98:99], v[172:173], v[28:29] op_sel_hi:[0,1,1]
	v_pk_fma_f32 v[30:31], v[98:99], v[174:175], v[30:31] op_sel_hi:[0,1,1]
	v_fmac_f32_e32 v2, v98, v193
	v_lshl_add_u64 v[32:33], v[32:33], 0, s[6:7]
	global_load_dword v98, v[32:33], off
	ds_read_b128 v[160:163], v5 offset:6080
	ds_read_b128 v[164:167], v5 offset:6096
	ds_read_b128 v[168:171], v5 offset:6112
	ds_read_b128 v[172:175], v5 offset:6128
	ds_read_b32 v193, v5 offset:6144
	s_waitcnt vmcnt(31) lgkmcnt(10)
	v_pk_fma_f32 v[16:17], v[100:101], v[176:177], v[16:17] op_sel_hi:[0,1,1]
	v_pk_fma_f32 v[18:19], v[100:101], v[178:179], v[18:19] op_sel_hi:[0,1,1]
	v_pk_fma_f32 v[20:21], v[100:101], v[180:181], v[20:21] op_sel_hi:[0,1,1]
	v_pk_fma_f32 v[22:23], v[100:101], v[182:183], v[22:23] op_sel_hi:[0,1,1]
	v_pk_fma_f32 v[24:25], v[100:101], v[184:185], v[24:25] op_sel_hi:[0,1,1]
	v_pk_fma_f32 v[26:27], v[100:101], v[186:187], v[26:27] op_sel_hi:[0,1,1]
	v_pk_fma_f32 v[28:29], v[100:101], v[188:189], v[28:29] op_sel_hi:[0,1,1]
	v_pk_fma_f32 v[30:31], v[100:101], v[190:191], v[30:31] op_sel_hi:[0,1,1]
	v_fmac_f32_e32 v2, v100, v194
	v_lshl_add_u64 v[32:33], v[32:33], 0, s[6:7]
	global_load_dword v100, v[32:33], off
	ds_read_b128 v[176:179], v5 offset:6160
	ds_read_b128 v[180:183], v5 offset:6176
	ds_read_b128 v[184:187], v5 offset:6192
	ds_read_b128 v[188:191], v5 offset:6208
	ds_read_b32 v194, v5 offset:6224
	s_waitcnt vmcnt(31) lgkmcnt(10)
	v_pk_fma_f32 v[16:17], v[102:103], v[144:145], v[16:17] op_sel_hi:[0,1,1]
	v_pk_fma_f32 v[18:19], v[102:103], v[146:147], v[18:19] op_sel_hi:[0,1,1]
	v_pk_fma_f32 v[20:21], v[102:103], v[148:149], v[20:21] op_sel_hi:[0,1,1]
	v_pk_fma_f32 v[22:23], v[102:103], v[150:151], v[22:23] op_sel_hi:[0,1,1]
	v_pk_fma_f32 v[24:25], v[102:103], v[152:153], v[24:25] op_sel_hi:[0,1,1]
	v_pk_fma_f32 v[26:27], v[102:103], v[154:155], v[26:27] op_sel_hi:[0,1,1]
	v_pk_fma_f32 v[28:29], v[102:103], v[156:157], v[28:29] op_sel_hi:[0,1,1]
	v_pk_fma_f32 v[30:31], v[102:103], v[158:159], v[30:31] op_sel_hi:[0,1,1]
	v_fmac_f32_e32 v2, v102, v192
	v_lshl_add_u64 v[32:33], v[32:33], 0, s[6:7]
	global_load_dword v102, v[32:33], off
	ds_read_b128 v[144:147], v5 offset:6240
	ds_read_b128 v[148:151], v5 offset:6256
	ds_read_b128 v[152:155], v5 offset:6272
	ds_read_b128 v[156:159], v5 offset:6288
	ds_read_b32 v192, v5 offset:6304
	s_waitcnt vmcnt(31) lgkmcnt(10)
	v_pk_fma_f32 v[16:17], v[104:105], v[160:161], v[16:17] op_sel_hi:[0,1,1]
	v_pk_fma_f32 v[18:19], v[104:105], v[162:163], v[18:19] op_sel_hi:[0,1,1]
	v_pk_fma_f32 v[20:21], v[104:105], v[164:165], v[20:21] op_sel_hi:[0,1,1]
	v_pk_fma_f32 v[22:23], v[104:105], v[166:167], v[22:23] op_sel_hi:[0,1,1]
	v_pk_fma_f32 v[24:25], v[104:105], v[168:169], v[24:25] op_sel_hi:[0,1,1]
	v_pk_fma_f32 v[26:27], v[104:105], v[170:171], v[26:27] op_sel_hi:[0,1,1]
	v_pk_fma_f32 v[28:29], v[104:105], v[172:173], v[28:29] op_sel_hi:[0,1,1]
	v_pk_fma_f32 v[30:31], v[104:105], v[174:175], v[30:31] op_sel_hi:[0,1,1]
	v_fmac_f32_e32 v2, v104, v193
	v_lshl_add_u64 v[32:33], v[32:33], 0, s[6:7]
	global_load_dword v104, v[32:33], off
	ds_read_b128 v[160:163], v5 offset:6320
	ds_read_b128 v[164:167], v5 offset:6336
	ds_read_b128 v[168:171], v5 offset:6352
	ds_read_b128 v[172:175], v5 offset:6368
	ds_read_b32 v193, v5 offset:6384
	s_waitcnt vmcnt(31) lgkmcnt(10)
	v_pk_fma_f32 v[16:17], v[106:107], v[176:177], v[16:17] op_sel_hi:[0,1,1]
	v_pk_fma_f32 v[18:19], v[106:107], v[178:179], v[18:19] op_sel_hi:[0,1,1]
	v_pk_fma_f32 v[20:21], v[106:107], v[180:181], v[20:21] op_sel_hi:[0,1,1]
	v_pk_fma_f32 v[22:23], v[106:107], v[182:183], v[22:23] op_sel_hi:[0,1,1]
	v_pk_fma_f32 v[24:25], v[106:107], v[184:185], v[24:25] op_sel_hi:[0,1,1]
	v_pk_fma_f32 v[26:27], v[106:107], v[186:187], v[26:27] op_sel_hi:[0,1,1]
	v_pk_fma_f32 v[28:29], v[106:107], v[188:189], v[28:29] op_sel_hi:[0,1,1]
	v_pk_fma_f32 v[30:31], v[106:107], v[190:191], v[30:31] op_sel_hi:[0,1,1]
	v_fmac_f32_e32 v2, v106, v194
	v_lshl_add_u64 v[32:33], v[32:33], 0, s[6:7]
	global_load_dword v106, v[32:33], off
	ds_read_b128 v[176:179], v5 offset:6400
	ds_read_b128 v[180:183], v5 offset:6416
	ds_read_b128 v[184:187], v5 offset:6432
	ds_read_b128 v[188:191], v5 offset:6448
	ds_read_b32 v194, v5 offset:6464
	s_waitcnt vmcnt(31) lgkmcnt(10)
	v_pk_fma_f32 v[16:17], v[108:109], v[144:145], v[16:17] op_sel_hi:[0,1,1]
	v_pk_fma_f32 v[18:19], v[108:109], v[146:147], v[18:19] op_sel_hi:[0,1,1]
	v_pk_fma_f32 v[20:21], v[108:109], v[148:149], v[20:21] op_sel_hi:[0,1,1]
	v_pk_fma_f32 v[22:23], v[108:109], v[150:151], v[22:23] op_sel_hi:[0,1,1]
	v_pk_fma_f32 v[24:25], v[108:109], v[152:153], v[24:25] op_sel_hi:[0,1,1]
	v_pk_fma_f32 v[26:27], v[108:109], v[154:155], v[26:27] op_sel_hi:[0,1,1]
	v_pk_fma_f32 v[28:29], v[108:109], v[156:157], v[28:29] op_sel_hi:[0,1,1]
	v_pk_fma_f32 v[30:31], v[108:109], v[158:159], v[30:31] op_sel_hi:[0,1,1]
	v_fmac_f32_e32 v2, v108, v192
	v_lshl_add_u64 v[32:33], v[32:33], 0, s[6:7]
	global_load_dword v108, v[32:33], off
	ds_read_b128 v[144:147], v5 offset:6480
	ds_read_b128 v[148:151], v5 offset:6496
	ds_read_b128 v[152:155], v5 offset:6512
	ds_read_b128 v[156:159], v5 offset:6528
	ds_read_b32 v192, v5 offset:6544
	s_waitcnt vmcnt(31) lgkmcnt(10)
	v_pk_fma_f32 v[16:17], v[110:111], v[160:161], v[16:17] op_sel_hi:[0,1,1]
	v_pk_fma_f32 v[18:19], v[110:111], v[162:163], v[18:19] op_sel_hi:[0,1,1]
	v_pk_fma_f32 v[20:21], v[110:111], v[164:165], v[20:21] op_sel_hi:[0,1,1]
	v_pk_fma_f32 v[22:23], v[110:111], v[166:167], v[22:23] op_sel_hi:[0,1,1]
	v_pk_fma_f32 v[24:25], v[110:111], v[168:169], v[24:25] op_sel_hi:[0,1,1]
	v_pk_fma_f32 v[26:27], v[110:111], v[170:171], v[26:27] op_sel_hi:[0,1,1]
	v_pk_fma_f32 v[28:29], v[110:111], v[172:173], v[28:29] op_sel_hi:[0,1,1]
	v_pk_fma_f32 v[30:31], v[110:111], v[174:175], v[30:31] op_sel_hi:[0,1,1]
	v_fmac_f32_e32 v2, v110, v193
	v_lshl_add_u64 v[32:33], v[32:33], 0, s[6:7]
	global_load_dword v110, v[32:33], off
	ds_read_b128 v[160:163], v5 offset:6560
	ds_read_b128 v[164:167], v5 offset:6576
	ds_read_b128 v[168:171], v5 offset:6592
	ds_read_b128 v[172:175], v5 offset:6608
	ds_read_b32 v193, v5 offset:6624
	s_waitcnt vmcnt(31) lgkmcnt(10)
	v_pk_fma_f32 v[16:17], v[112:113], v[176:177], v[16:17] op_sel_hi:[0,1,1]
	v_pk_fma_f32 v[18:19], v[112:113], v[178:179], v[18:19] op_sel_hi:[0,1,1]
	v_pk_fma_f32 v[20:21], v[112:113], v[180:181], v[20:21] op_sel_hi:[0,1,1]
	v_pk_fma_f32 v[22:23], v[112:113], v[182:183], v[22:23] op_sel_hi:[0,1,1]
	v_pk_fma_f32 v[24:25], v[112:113], v[184:185], v[24:25] op_sel_hi:[0,1,1]
	v_pk_fma_f32 v[26:27], v[112:113], v[186:187], v[26:27] op_sel_hi:[0,1,1]
	v_pk_fma_f32 v[28:29], v[112:113], v[188:189], v[28:29] op_sel_hi:[0,1,1]
	v_pk_fma_f32 v[30:31], v[112:113], v[190:191], v[30:31] op_sel_hi:[0,1,1]
	v_fmac_f32_e32 v2, v112, v194
	v_lshl_add_u64 v[32:33], v[32:33], 0, s[6:7]
	global_load_dword v112, v[32:33], off
	ds_read_b128 v[176:179], v5 offset:6640
	ds_read_b128 v[180:183], v5 offset:6656
	ds_read_b128 v[184:187], v5 offset:6672
	ds_read_b128 v[188:191], v5 offset:6688
	ds_read_b32 v194, v5 offset:6704
	s_waitcnt vmcnt(31) lgkmcnt(10)
	v_pk_fma_f32 v[16:17], v[114:115], v[144:145], v[16:17] op_sel_hi:[0,1,1]
	v_pk_fma_f32 v[18:19], v[114:115], v[146:147], v[18:19] op_sel_hi:[0,1,1]
	v_pk_fma_f32 v[20:21], v[114:115], v[148:149], v[20:21] op_sel_hi:[0,1,1]
	v_pk_fma_f32 v[22:23], v[114:115], v[150:151], v[22:23] op_sel_hi:[0,1,1]
	v_pk_fma_f32 v[24:25], v[114:115], v[152:153], v[24:25] op_sel_hi:[0,1,1]
	v_pk_fma_f32 v[26:27], v[114:115], v[154:155], v[26:27] op_sel_hi:[0,1,1]
	v_pk_fma_f32 v[28:29], v[114:115], v[156:157], v[28:29] op_sel_hi:[0,1,1]
	v_pk_fma_f32 v[30:31], v[114:115], v[158:159], v[30:31] op_sel_hi:[0,1,1]
	v_fmac_f32_e32 v2, v114, v192
	v_lshl_add_u64 v[32:33], v[32:33], 0, s[6:7]
	global_load_dword v114, v[32:33], off
	ds_read_b128 v[144:147], v5 offset:6720
	ds_read_b128 v[148:151], v5 offset:6736
	ds_read_b128 v[152:155], v5 offset:6752
	ds_read_b128 v[156:159], v5 offset:6768
	ds_read_b32 v192, v5 offset:6784
	s_waitcnt vmcnt(31) lgkmcnt(10)
	v_pk_fma_f32 v[16:17], v[116:117], v[160:161], v[16:17] op_sel_hi:[0,1,1]
	v_pk_fma_f32 v[18:19], v[116:117], v[162:163], v[18:19] op_sel_hi:[0,1,1]
	v_pk_fma_f32 v[20:21], v[116:117], v[164:165], v[20:21] op_sel_hi:[0,1,1]
	v_pk_fma_f32 v[22:23], v[116:117], v[166:167], v[22:23] op_sel_hi:[0,1,1]
	v_pk_fma_f32 v[24:25], v[116:117], v[168:169], v[24:25] op_sel_hi:[0,1,1]
	v_pk_fma_f32 v[26:27], v[116:117], v[170:171], v[26:27] op_sel_hi:[0,1,1]
	v_pk_fma_f32 v[28:29], v[116:117], v[172:173], v[28:29] op_sel_hi:[0,1,1]
	v_pk_fma_f32 v[30:31], v[116:117], v[174:175], v[30:31] op_sel_hi:[0,1,1]
	v_fmac_f32_e32 v2, v116, v193
	v_lshl_add_u64 v[32:33], v[32:33], 0, s[6:7]
	global_load_dword v116, v[32:33], off
	ds_read_b128 v[160:163], v5 offset:6800
	ds_read_b128 v[164:167], v5 offset:6816
	ds_read_b128 v[168:171], v5 offset:6832
	ds_read_b128 v[172:175], v5 offset:6848
	ds_read_b32 v193, v5 offset:6864
	s_waitcnt vmcnt(31) lgkmcnt(10)
	v_pk_fma_f32 v[16:17], v[118:119], v[176:177], v[16:17] op_sel_hi:[0,1,1]
	v_pk_fma_f32 v[18:19], v[118:119], v[178:179], v[18:19] op_sel_hi:[0,1,1]
	v_pk_fma_f32 v[20:21], v[118:119], v[180:181], v[20:21] op_sel_hi:[0,1,1]
	v_pk_fma_f32 v[22:23], v[118:119], v[182:183], v[22:23] op_sel_hi:[0,1,1]
	v_pk_fma_f32 v[24:25], v[118:119], v[184:185], v[24:25] op_sel_hi:[0,1,1]
	v_pk_fma_f32 v[26:27], v[118:119], v[186:187], v[26:27] op_sel_hi:[0,1,1]
	v_pk_fma_f32 v[28:29], v[118:119], v[188:189], v[28:29] op_sel_hi:[0,1,1]
	v_pk_fma_f32 v[30:31], v[118:119], v[190:191], v[30:31] op_sel_hi:[0,1,1]
	v_fmac_f32_e32 v2, v118, v194
	v_lshl_add_u64 v[32:33], v[32:33], 0, s[6:7]
	global_load_dword v118, v[32:33], off
	ds_read_b128 v[176:179], v5 offset:6880
	ds_read_b128 v[180:183], v5 offset:6896
	ds_read_b128 v[184:187], v5 offset:6912
	ds_read_b128 v[188:191], v5 offset:6928
	ds_read_b32 v194, v5 offset:6944
	s_waitcnt vmcnt(31) lgkmcnt(10)
	v_pk_fma_f32 v[16:17], v[120:121], v[144:145], v[16:17] op_sel_hi:[0,1,1]
	v_pk_fma_f32 v[18:19], v[120:121], v[146:147], v[18:19] op_sel_hi:[0,1,1]
	v_pk_fma_f32 v[20:21], v[120:121], v[148:149], v[20:21] op_sel_hi:[0,1,1]
	v_pk_fma_f32 v[22:23], v[120:121], v[150:151], v[22:23] op_sel_hi:[0,1,1]
	v_pk_fma_f32 v[24:25], v[120:121], v[152:153], v[24:25] op_sel_hi:[0,1,1]
	v_pk_fma_f32 v[26:27], v[120:121], v[154:155], v[26:27] op_sel_hi:[0,1,1]
	v_pk_fma_f32 v[28:29], v[120:121], v[156:157], v[28:29] op_sel_hi:[0,1,1]
	v_pk_fma_f32 v[30:31], v[120:121], v[158:159], v[30:31] op_sel_hi:[0,1,1]
	v_fmac_f32_e32 v2, v120, v192
	v_lshl_add_u64 v[32:33], v[32:33], 0, s[6:7]
	global_load_dword v120, v[32:33], off
	ds_read_b128 v[144:147], v5 offset:6960
	ds_read_b128 v[148:151], v5 offset:6976
	ds_read_b128 v[152:155], v5 offset:6992
	ds_read_b128 v[156:159], v5 offset:7008
	ds_read_b32 v192, v5 offset:7024
	s_waitcnt vmcnt(31) lgkmcnt(10)
	v_pk_fma_f32 v[16:17], v[122:123], v[160:161], v[16:17] op_sel_hi:[0,1,1]
	v_pk_fma_f32 v[18:19], v[122:123], v[162:163], v[18:19] op_sel_hi:[0,1,1]
	v_pk_fma_f32 v[20:21], v[122:123], v[164:165], v[20:21] op_sel_hi:[0,1,1]
	v_pk_fma_f32 v[22:23], v[122:123], v[166:167], v[22:23] op_sel_hi:[0,1,1]
	v_pk_fma_f32 v[24:25], v[122:123], v[168:169], v[24:25] op_sel_hi:[0,1,1]
	v_pk_fma_f32 v[26:27], v[122:123], v[170:171], v[26:27] op_sel_hi:[0,1,1]
	v_pk_fma_f32 v[28:29], v[122:123], v[172:173], v[28:29] op_sel_hi:[0,1,1]
	v_pk_fma_f32 v[30:31], v[122:123], v[174:175], v[30:31] op_sel_hi:[0,1,1]
	v_fmac_f32_e32 v2, v122, v193
	v_lshl_add_u64 v[32:33], v[32:33], 0, s[6:7]
	global_load_dword v122, v[32:33], off
	ds_read_b128 v[160:163], v5 offset:7040
	ds_read_b128 v[164:167], v5 offset:7056
	ds_read_b128 v[168:171], v5 offset:7072
	ds_read_b128 v[172:175], v5 offset:7088
	ds_read_b32 v193, v5 offset:7104
	s_waitcnt vmcnt(31) lgkmcnt(10)
	v_pk_fma_f32 v[16:17], v[124:125], v[176:177], v[16:17] op_sel_hi:[0,1,1]
	v_pk_fma_f32 v[18:19], v[124:125], v[178:179], v[18:19] op_sel_hi:[0,1,1]
	v_pk_fma_f32 v[20:21], v[124:125], v[180:181], v[20:21] op_sel_hi:[0,1,1]
	v_pk_fma_f32 v[22:23], v[124:125], v[182:183], v[22:23] op_sel_hi:[0,1,1]
	v_pk_fma_f32 v[24:25], v[124:125], v[184:185], v[24:25] op_sel_hi:[0,1,1]
	v_pk_fma_f32 v[26:27], v[124:125], v[186:187], v[26:27] op_sel_hi:[0,1,1]
	v_pk_fma_f32 v[28:29], v[124:125], v[188:189], v[28:29] op_sel_hi:[0,1,1]
	v_pk_fma_f32 v[30:31], v[124:125], v[190:191], v[30:31] op_sel_hi:[0,1,1]
	v_fmac_f32_e32 v2, v124, v194
	v_lshl_add_u64 v[32:33], v[32:33], 0, s[6:7]
	global_load_dword v124, v[32:33], off
	ds_read_b128 v[176:179], v5 offset:7120
	ds_read_b128 v[180:183], v5 offset:7136
	ds_read_b128 v[184:187], v5 offset:7152
	ds_read_b128 v[188:191], v5 offset:7168
	ds_read_b32 v194, v5 offset:7184
	s_waitcnt vmcnt(31) lgkmcnt(10)
	v_pk_fma_f32 v[16:17], v[126:127], v[144:145], v[16:17] op_sel_hi:[0,1,1]
	v_pk_fma_f32 v[18:19], v[126:127], v[146:147], v[18:19] op_sel_hi:[0,1,1]
	v_pk_fma_f32 v[20:21], v[126:127], v[148:149], v[20:21] op_sel_hi:[0,1,1]
	v_pk_fma_f32 v[22:23], v[126:127], v[150:151], v[22:23] op_sel_hi:[0,1,1]
	v_pk_fma_f32 v[24:25], v[126:127], v[152:153], v[24:25] op_sel_hi:[0,1,1]
	v_pk_fma_f32 v[26:27], v[126:127], v[154:155], v[26:27] op_sel_hi:[0,1,1]
	v_pk_fma_f32 v[28:29], v[126:127], v[156:157], v[28:29] op_sel_hi:[0,1,1]
	v_pk_fma_f32 v[30:31], v[126:127], v[158:159], v[30:31] op_sel_hi:[0,1,1]
	v_fmac_f32_e32 v2, v126, v192
	v_lshl_add_u64 v[32:33], v[32:33], 0, s[6:7]
	global_load_dword v126, v[32:33], off
	ds_read_b128 v[144:147], v5 offset:7200
	ds_read_b128 v[148:151], v5 offset:7216
	ds_read_b128 v[152:155], v5 offset:7232
	ds_read_b128 v[156:159], v5 offset:7248
	ds_read_b32 v192, v5 offset:7264
	s_waitcnt vmcnt(31) lgkmcnt(10)
	v_pk_fma_f32 v[16:17], v[128:129], v[160:161], v[16:17] op_sel_hi:[0,1,1]
	v_pk_fma_f32 v[18:19], v[128:129], v[162:163], v[18:19] op_sel_hi:[0,1,1]
	v_pk_fma_f32 v[20:21], v[128:129], v[164:165], v[20:21] op_sel_hi:[0,1,1]
	v_pk_fma_f32 v[22:23], v[128:129], v[166:167], v[22:23] op_sel_hi:[0,1,1]
	v_pk_fma_f32 v[24:25], v[128:129], v[168:169], v[24:25] op_sel_hi:[0,1,1]
	v_pk_fma_f32 v[26:27], v[128:129], v[170:171], v[26:27] op_sel_hi:[0,1,1]
	v_pk_fma_f32 v[28:29], v[128:129], v[172:173], v[28:29] op_sel_hi:[0,1,1]
	v_pk_fma_f32 v[30:31], v[128:129], v[174:175], v[30:31] op_sel_hi:[0,1,1]
	v_fmac_f32_e32 v2, v128, v193
	v_lshl_add_u64 v[32:33], v[32:33], 0, s[6:7]
	global_load_dword v128, v[32:33], off
	ds_read_b128 v[160:163], v5 offset:7280
	ds_read_b128 v[164:167], v5 offset:7296
	ds_read_b128 v[168:171], v5 offset:7312
	ds_read_b128 v[172:175], v5 offset:7328
	ds_read_b32 v193, v5 offset:7344
	s_waitcnt vmcnt(31) lgkmcnt(10)
	v_pk_fma_f32 v[16:17], v[130:131], v[176:177], v[16:17] op_sel_hi:[0,1,1]
	v_pk_fma_f32 v[18:19], v[130:131], v[178:179], v[18:19] op_sel_hi:[0,1,1]
	v_pk_fma_f32 v[20:21], v[130:131], v[180:181], v[20:21] op_sel_hi:[0,1,1]
	v_pk_fma_f32 v[22:23], v[130:131], v[182:183], v[22:23] op_sel_hi:[0,1,1]
	v_pk_fma_f32 v[24:25], v[130:131], v[184:185], v[24:25] op_sel_hi:[0,1,1]
	v_pk_fma_f32 v[26:27], v[130:131], v[186:187], v[26:27] op_sel_hi:[0,1,1]
	v_pk_fma_f32 v[28:29], v[130:131], v[188:189], v[28:29] op_sel_hi:[0,1,1]
	v_pk_fma_f32 v[30:31], v[130:131], v[190:191], v[30:31] op_sel_hi:[0,1,1]
	v_fmac_f32_e32 v2, v130, v194
	v_lshl_add_u64 v[32:33], v[32:33], 0, s[6:7]
	global_load_dword v130, v[32:33], off
	ds_read_b128 v[176:179], v5 offset:7360
	ds_read_b128 v[180:183], v5 offset:7376
	ds_read_b128 v[184:187], v5 offset:7392
	ds_read_b128 v[188:191], v5 offset:7408
	ds_read_b32 v194, v5 offset:7424
	s_waitcnt vmcnt(31) lgkmcnt(10)
	v_pk_fma_f32 v[16:17], v[132:133], v[144:145], v[16:17] op_sel_hi:[0,1,1]
	v_pk_fma_f32 v[18:19], v[132:133], v[146:147], v[18:19] op_sel_hi:[0,1,1]
	v_pk_fma_f32 v[20:21], v[132:133], v[148:149], v[20:21] op_sel_hi:[0,1,1]
	v_pk_fma_f32 v[22:23], v[132:133], v[150:151], v[22:23] op_sel_hi:[0,1,1]
	v_pk_fma_f32 v[24:25], v[132:133], v[152:153], v[24:25] op_sel_hi:[0,1,1]
	v_pk_fma_f32 v[26:27], v[132:133], v[154:155], v[26:27] op_sel_hi:[0,1,1]
	v_pk_fma_f32 v[28:29], v[132:133], v[156:157], v[28:29] op_sel_hi:[0,1,1]
	v_pk_fma_f32 v[30:31], v[132:133], v[158:159], v[30:31] op_sel_hi:[0,1,1]
	v_fmac_f32_e32 v2, v132, v192
	v_lshl_add_u64 v[32:33], v[32:33], 0, s[6:7]
	global_load_dword v132, v[32:33], off
	ds_read_b128 v[144:147], v5 offset:7440
	ds_read_b128 v[148:151], v5 offset:7456
	ds_read_b128 v[152:155], v5 offset:7472
	ds_read_b128 v[156:159], v5 offset:7488
	ds_read_b32 v192, v5 offset:7504
	s_waitcnt vmcnt(31) lgkmcnt(10)
	v_pk_fma_f32 v[16:17], v[134:135], v[160:161], v[16:17] op_sel_hi:[0,1,1]
	v_pk_fma_f32 v[18:19], v[134:135], v[162:163], v[18:19] op_sel_hi:[0,1,1]
	v_pk_fma_f32 v[20:21], v[134:135], v[164:165], v[20:21] op_sel_hi:[0,1,1]
	v_pk_fma_f32 v[22:23], v[134:135], v[166:167], v[22:23] op_sel_hi:[0,1,1]
	v_pk_fma_f32 v[24:25], v[134:135], v[168:169], v[24:25] op_sel_hi:[0,1,1]
	v_pk_fma_f32 v[26:27], v[134:135], v[170:171], v[26:27] op_sel_hi:[0,1,1]
	v_pk_fma_f32 v[28:29], v[134:135], v[172:173], v[28:29] op_sel_hi:[0,1,1]
	v_pk_fma_f32 v[30:31], v[134:135], v[174:175], v[30:31] op_sel_hi:[0,1,1]
	v_fmac_f32_e32 v2, v134, v193
	v_lshl_add_u64 v[32:33], v[32:33], 0, s[6:7]
	global_load_dword v134, v[32:33], off
	ds_read_b128 v[160:163], v5 offset:7520
	ds_read_b128 v[164:167], v5 offset:7536
	ds_read_b128 v[168:171], v5 offset:7552
	ds_read_b128 v[172:175], v5 offset:7568
	ds_read_b32 v193, v5 offset:7584
	s_waitcnt vmcnt(31) lgkmcnt(10)
	v_pk_fma_f32 v[16:17], v[136:137], v[176:177], v[16:17] op_sel_hi:[0,1,1]
	v_pk_fma_f32 v[18:19], v[136:137], v[178:179], v[18:19] op_sel_hi:[0,1,1]
	v_pk_fma_f32 v[20:21], v[136:137], v[180:181], v[20:21] op_sel_hi:[0,1,1]
	v_pk_fma_f32 v[22:23], v[136:137], v[182:183], v[22:23] op_sel_hi:[0,1,1]
	v_pk_fma_f32 v[24:25], v[136:137], v[184:185], v[24:25] op_sel_hi:[0,1,1]
	v_pk_fma_f32 v[26:27], v[136:137], v[186:187], v[26:27] op_sel_hi:[0,1,1]
	v_pk_fma_f32 v[28:29], v[136:137], v[188:189], v[28:29] op_sel_hi:[0,1,1]
	v_pk_fma_f32 v[30:31], v[136:137], v[190:191], v[30:31] op_sel_hi:[0,1,1]
	v_fmac_f32_e32 v2, v136, v194
	v_lshl_add_u64 v[32:33], v[32:33], 0, s[6:7]
	global_load_dword v136, v[32:33], off
	ds_read_b128 v[176:179], v5 offset:7600
	ds_read_b128 v[180:183], v5 offset:7616
	ds_read_b128 v[184:187], v5 offset:7632
	ds_read_b128 v[188:191], v5 offset:7648
	ds_read_b32 v194, v5 offset:7664
	s_waitcnt vmcnt(31) lgkmcnt(10)
	v_pk_fma_f32 v[16:17], v[138:139], v[144:145], v[16:17] op_sel_hi:[0,1,1]
	v_pk_fma_f32 v[18:19], v[138:139], v[146:147], v[18:19] op_sel_hi:[0,1,1]
	v_pk_fma_f32 v[20:21], v[138:139], v[148:149], v[20:21] op_sel_hi:[0,1,1]
	v_pk_fma_f32 v[22:23], v[138:139], v[150:151], v[22:23] op_sel_hi:[0,1,1]
	v_pk_fma_f32 v[24:25], v[138:139], v[152:153], v[24:25] op_sel_hi:[0,1,1]
	v_pk_fma_f32 v[26:27], v[138:139], v[154:155], v[26:27] op_sel_hi:[0,1,1]
	v_pk_fma_f32 v[28:29], v[138:139], v[156:157], v[28:29] op_sel_hi:[0,1,1]
	v_pk_fma_f32 v[30:31], v[138:139], v[158:159], v[30:31] op_sel_hi:[0,1,1]
	v_fmac_f32_e32 v2, v138, v192
	v_lshl_add_u64 v[32:33], v[32:33], 0, s[6:7]
	global_load_dword v138, v[32:33], off
	ds_read_b128 v[144:147], v5 offset:7680
	ds_read_b128 v[148:151], v5 offset:7696
	ds_read_b128 v[152:155], v5 offset:7712
	ds_read_b128 v[156:159], v5 offset:7728
	ds_read_b32 v192, v5 offset:7744
	s_waitcnt vmcnt(31) lgkmcnt(10)
	v_pk_fma_f32 v[16:17], v[140:141], v[160:161], v[16:17] op_sel_hi:[0,1,1]
	v_pk_fma_f32 v[18:19], v[140:141], v[162:163], v[18:19] op_sel_hi:[0,1,1]
	v_pk_fma_f32 v[20:21], v[140:141], v[164:165], v[20:21] op_sel_hi:[0,1,1]
	v_pk_fma_f32 v[22:23], v[140:141], v[166:167], v[22:23] op_sel_hi:[0,1,1]
	v_pk_fma_f32 v[24:25], v[140:141], v[168:169], v[24:25] op_sel_hi:[0,1,1]
	v_pk_fma_f32 v[26:27], v[140:141], v[170:171], v[26:27] op_sel_hi:[0,1,1]
	v_pk_fma_f32 v[28:29], v[140:141], v[172:173], v[28:29] op_sel_hi:[0,1,1]
	v_pk_fma_f32 v[30:31], v[140:141], v[174:175], v[30:31] op_sel_hi:[0,1,1]
	v_fmac_f32_e32 v2, v140, v193
	v_lshl_add_u64 v[32:33], v[32:33], 0, s[6:7]
	global_load_dword v140, v[32:33], off
	ds_read_b128 v[160:163], v5 offset:7760
	ds_read_b128 v[164:167], v5 offset:7776
	ds_read_b128 v[168:171], v5 offset:7792
	ds_read_b128 v[172:175], v5 offset:7808
	ds_read_b32 v193, v5 offset:7824
	s_waitcnt vmcnt(31) lgkmcnt(10)
	v_pk_fma_f32 v[16:17], v[142:143], v[176:177], v[16:17] op_sel_hi:[0,1,1]
	v_pk_fma_f32 v[18:19], v[142:143], v[178:179], v[18:19] op_sel_hi:[0,1,1]
	v_pk_fma_f32 v[20:21], v[142:143], v[180:181], v[20:21] op_sel_hi:[0,1,1]
	v_pk_fma_f32 v[22:23], v[142:143], v[182:183], v[22:23] op_sel_hi:[0,1,1]
	v_pk_fma_f32 v[24:25], v[142:143], v[184:185], v[24:25] op_sel_hi:[0,1,1]
	v_pk_fma_f32 v[26:27], v[142:143], v[186:187], v[26:27] op_sel_hi:[0,1,1]
	v_pk_fma_f32 v[28:29], v[142:143], v[188:189], v[28:29] op_sel_hi:[0,1,1]
	v_pk_fma_f32 v[30:31], v[142:143], v[190:191], v[30:31] op_sel_hi:[0,1,1]
	v_fmac_f32_e32 v2, v142, v194
	v_lshl_add_u64 v[32:33], v[32:33], 0, s[6:7]
	global_load_dword v142, v[32:33], off
	ds_read_b128 v[176:179], v5 offset:7840
	ds_read_b128 v[180:183], v5 offset:7856
	ds_read_b128 v[184:187], v5 offset:7872
	ds_read_b128 v[188:191], v5 offset:7888
	ds_read_b32 v194, v5 offset:7904
	s_waitcnt vmcnt(31) lgkmcnt(10)
	v_pk_fma_f32 v[16:17], v[80:81], v[144:145], v[16:17] op_sel_hi:[0,1,1]
	v_pk_fma_f32 v[18:19], v[80:81], v[146:147], v[18:19] op_sel_hi:[0,1,1]
	v_pk_fma_f32 v[20:21], v[80:81], v[148:149], v[20:21] op_sel_hi:[0,1,1]
	v_pk_fma_f32 v[22:23], v[80:81], v[150:151], v[22:23] op_sel_hi:[0,1,1]
	v_pk_fma_f32 v[24:25], v[80:81], v[152:153], v[24:25] op_sel_hi:[0,1,1]
	v_pk_fma_f32 v[26:27], v[80:81], v[154:155], v[26:27] op_sel_hi:[0,1,1]
	v_pk_fma_f32 v[28:29], v[80:81], v[156:157], v[28:29] op_sel_hi:[0,1,1]
	v_pk_fma_f32 v[30:31], v[80:81], v[158:159], v[30:31] op_sel_hi:[0,1,1]
	v_fmac_f32_e32 v2, v80, v192
	ds_read_b128 v[144:147], v5 offset:7920
	ds_read_b128 v[148:151], v5 offset:7936
	ds_read_b128 v[152:155], v5 offset:7952
	ds_read_b128 v[156:159], v5 offset:7968
	ds_read_b32 v192, v5 offset:7984
	s_waitcnt vmcnt(30) lgkmcnt(10)
	v_pk_fma_f32 v[16:17], v[82:83], v[160:161], v[16:17] op_sel_hi:[0,1,1]
	v_pk_fma_f32 v[18:19], v[82:83], v[162:163], v[18:19] op_sel_hi:[0,1,1]
	v_pk_fma_f32 v[20:21], v[82:83], v[164:165], v[20:21] op_sel_hi:[0,1,1]
	v_pk_fma_f32 v[22:23], v[82:83], v[166:167], v[22:23] op_sel_hi:[0,1,1]
	v_pk_fma_f32 v[24:25], v[82:83], v[168:169], v[24:25] op_sel_hi:[0,1,1]
	v_pk_fma_f32 v[26:27], v[82:83], v[170:171], v[26:27] op_sel_hi:[0,1,1]
	v_pk_fma_f32 v[28:29], v[82:83], v[172:173], v[28:29] op_sel_hi:[0,1,1]
	v_pk_fma_f32 v[30:31], v[82:83], v[174:175], v[30:31] op_sel_hi:[0,1,1]
	v_fmac_f32_e32 v2, v82, v193
	ds_read_b128 v[160:163], v5 offset:8000
	ds_read_b128 v[164:167], v5 offset:8016
	ds_read_b128 v[168:171], v5 offset:8032
	ds_read_b128 v[172:175], v5 offset:8048
	ds_read_b32 v193, v5 offset:8064
	s_waitcnt vmcnt(29) lgkmcnt(10)
	v_pk_fma_f32 v[16:17], v[84:85], v[176:177], v[16:17] op_sel_hi:[0,1,1]
	v_pk_fma_f32 v[18:19], v[84:85], v[178:179], v[18:19] op_sel_hi:[0,1,1]
	v_pk_fma_f32 v[20:21], v[84:85], v[180:181], v[20:21] op_sel_hi:[0,1,1]
	v_pk_fma_f32 v[22:23], v[84:85], v[182:183], v[22:23] op_sel_hi:[0,1,1]
	v_pk_fma_f32 v[24:25], v[84:85], v[184:185], v[24:25] op_sel_hi:[0,1,1]
	v_pk_fma_f32 v[26:27], v[84:85], v[186:187], v[26:27] op_sel_hi:[0,1,1]
	v_pk_fma_f32 v[28:29], v[84:85], v[188:189], v[28:29] op_sel_hi:[0,1,1]
	v_pk_fma_f32 v[30:31], v[84:85], v[190:191], v[30:31] op_sel_hi:[0,1,1]
	v_fmac_f32_e32 v2, v84, v194
	ds_read_b128 v[176:179], v5 offset:8080
	ds_read_b128 v[180:183], v5 offset:8096
	ds_read_b128 v[184:187], v5 offset:8112
	ds_read_b128 v[188:191], v5 offset:8128
	ds_read_b32 v194, v5 offset:8144
	s_waitcnt vmcnt(28) lgkmcnt(10)
	v_pk_fma_f32 v[16:17], v[86:87], v[144:145], v[16:17] op_sel_hi:[0,1,1]
	v_pk_fma_f32 v[18:19], v[86:87], v[146:147], v[18:19] op_sel_hi:[0,1,1]
	v_pk_fma_f32 v[20:21], v[86:87], v[148:149], v[20:21] op_sel_hi:[0,1,1]
	v_pk_fma_f32 v[22:23], v[86:87], v[150:151], v[22:23] op_sel_hi:[0,1,1]
	v_pk_fma_f32 v[24:25], v[86:87], v[152:153], v[24:25] op_sel_hi:[0,1,1]
	v_pk_fma_f32 v[26:27], v[86:87], v[154:155], v[26:27] op_sel_hi:[0,1,1]
	v_pk_fma_f32 v[28:29], v[86:87], v[156:157], v[28:29] op_sel_hi:[0,1,1]
	v_pk_fma_f32 v[30:31], v[86:87], v[158:159], v[30:31] op_sel_hi:[0,1,1]
	v_fmac_f32_e32 v2, v86, v192
	ds_read_b128 v[144:147], v5 offset:8160
	ds_read_b128 v[148:151], v5 offset:8176
	ds_read_b128 v[152:155], v5 offset:8192
	ds_read_b128 v[156:159], v5 offset:8208
	ds_read_b32 v192, v5 offset:8224
	s_waitcnt vmcnt(27) lgkmcnt(10)
	v_pk_fma_f32 v[16:17], v[88:89], v[160:161], v[16:17] op_sel_hi:[0,1,1]
	v_pk_fma_f32 v[18:19], v[88:89], v[162:163], v[18:19] op_sel_hi:[0,1,1]
	v_pk_fma_f32 v[20:21], v[88:89], v[164:165], v[20:21] op_sel_hi:[0,1,1]
	v_pk_fma_f32 v[22:23], v[88:89], v[166:167], v[22:23] op_sel_hi:[0,1,1]
	v_pk_fma_f32 v[24:25], v[88:89], v[168:169], v[24:25] op_sel_hi:[0,1,1]
	v_pk_fma_f32 v[26:27], v[88:89], v[170:171], v[26:27] op_sel_hi:[0,1,1]
	v_pk_fma_f32 v[28:29], v[88:89], v[172:173], v[28:29] op_sel_hi:[0,1,1]
	v_pk_fma_f32 v[30:31], v[88:89], v[174:175], v[30:31] op_sel_hi:[0,1,1]
	v_fmac_f32_e32 v2, v88, v193
	ds_read_b128 v[160:163], v5 offset:8240
	ds_read_b128 v[164:167], v5 offset:8256
	ds_read_b128 v[168:171], v5 offset:8272
	ds_read_b128 v[172:175], v5 offset:8288
	ds_read_b32 v193, v5 offset:8304
	s_waitcnt vmcnt(26) lgkmcnt(10)
	v_pk_fma_f32 v[16:17], v[90:91], v[176:177], v[16:17] op_sel_hi:[0,1,1]
	v_pk_fma_f32 v[18:19], v[90:91], v[178:179], v[18:19] op_sel_hi:[0,1,1]
	v_pk_fma_f32 v[20:21], v[90:91], v[180:181], v[20:21] op_sel_hi:[0,1,1]
	v_pk_fma_f32 v[22:23], v[90:91], v[182:183], v[22:23] op_sel_hi:[0,1,1]
	v_pk_fma_f32 v[24:25], v[90:91], v[184:185], v[24:25] op_sel_hi:[0,1,1]
	v_pk_fma_f32 v[26:27], v[90:91], v[186:187], v[26:27] op_sel_hi:[0,1,1]
	v_pk_fma_f32 v[28:29], v[90:91], v[188:189], v[28:29] op_sel_hi:[0,1,1]
	v_pk_fma_f32 v[30:31], v[90:91], v[190:191], v[30:31] op_sel_hi:[0,1,1]
	v_fmac_f32_e32 v2, v90, v194
	ds_read_b128 v[176:179], v5 offset:8320
	ds_read_b128 v[180:183], v5 offset:8336
	ds_read_b128 v[184:187], v5 offset:8352
	ds_read_b128 v[188:191], v5 offset:8368
	ds_read_b32 v194, v5 offset:8384
	s_waitcnt vmcnt(25) lgkmcnt(10)
	v_pk_fma_f32 v[16:17], v[92:93], v[144:145], v[16:17] op_sel_hi:[0,1,1]
	v_pk_fma_f32 v[18:19], v[92:93], v[146:147], v[18:19] op_sel_hi:[0,1,1]
	v_pk_fma_f32 v[20:21], v[92:93], v[148:149], v[20:21] op_sel_hi:[0,1,1]
	v_pk_fma_f32 v[22:23], v[92:93], v[150:151], v[22:23] op_sel_hi:[0,1,1]
	v_pk_fma_f32 v[24:25], v[92:93], v[152:153], v[24:25] op_sel_hi:[0,1,1]
	v_pk_fma_f32 v[26:27], v[92:93], v[154:155], v[26:27] op_sel_hi:[0,1,1]
	v_pk_fma_f32 v[28:29], v[92:93], v[156:157], v[28:29] op_sel_hi:[0,1,1]
	v_pk_fma_f32 v[30:31], v[92:93], v[158:159], v[30:31] op_sel_hi:[0,1,1]
	v_fmac_f32_e32 v2, v92, v192
	ds_read_b128 v[144:147], v5 offset:8400
	ds_read_b128 v[148:151], v5 offset:8416
	ds_read_b128 v[152:155], v5 offset:8432
	ds_read_b128 v[156:159], v5 offset:8448
	ds_read_b32 v192, v5 offset:8464
	s_waitcnt vmcnt(24) lgkmcnt(10)
	v_pk_fma_f32 v[16:17], v[94:95], v[160:161], v[16:17] op_sel_hi:[0,1,1]
	v_pk_fma_f32 v[18:19], v[94:95], v[162:163], v[18:19] op_sel_hi:[0,1,1]
	v_pk_fma_f32 v[20:21], v[94:95], v[164:165], v[20:21] op_sel_hi:[0,1,1]
	v_pk_fma_f32 v[22:23], v[94:95], v[166:167], v[22:23] op_sel_hi:[0,1,1]
	v_pk_fma_f32 v[24:25], v[94:95], v[168:169], v[24:25] op_sel_hi:[0,1,1]
	v_pk_fma_f32 v[26:27], v[94:95], v[170:171], v[26:27] op_sel_hi:[0,1,1]
	v_pk_fma_f32 v[28:29], v[94:95], v[172:173], v[28:29] op_sel_hi:[0,1,1]
	v_pk_fma_f32 v[30:31], v[94:95], v[174:175], v[30:31] op_sel_hi:[0,1,1]
	v_fmac_f32_e32 v2, v94, v193
	ds_read_b128 v[160:163], v5 offset:8480
	ds_read_b128 v[164:167], v5 offset:8496
	ds_read_b128 v[168:171], v5 offset:8512
	ds_read_b128 v[172:175], v5 offset:8528
	ds_read_b32 v193, v5 offset:8544
	s_waitcnt vmcnt(23) lgkmcnt(10)
	v_pk_fma_f32 v[16:17], v[96:97], v[176:177], v[16:17] op_sel_hi:[0,1,1]
	v_pk_fma_f32 v[18:19], v[96:97], v[178:179], v[18:19] op_sel_hi:[0,1,1]
	v_pk_fma_f32 v[20:21], v[96:97], v[180:181], v[20:21] op_sel_hi:[0,1,1]
	v_pk_fma_f32 v[22:23], v[96:97], v[182:183], v[22:23] op_sel_hi:[0,1,1]
	v_pk_fma_f32 v[24:25], v[96:97], v[184:185], v[24:25] op_sel_hi:[0,1,1]
	v_pk_fma_f32 v[26:27], v[96:97], v[186:187], v[26:27] op_sel_hi:[0,1,1]
	v_pk_fma_f32 v[28:29], v[96:97], v[188:189], v[28:29] op_sel_hi:[0,1,1]
	v_pk_fma_f32 v[30:31], v[96:97], v[190:191], v[30:31] op_sel_hi:[0,1,1]
	v_fmac_f32_e32 v2, v96, v194
	ds_read_b128 v[176:179], v5 offset:8560
	ds_read_b128 v[180:183], v5 offset:8576
	ds_read_b128 v[184:187], v5 offset:8592
	ds_read_b128 v[188:191], v5 offset:8608
	ds_read_b32 v194, v5 offset:8624
	s_waitcnt vmcnt(22) lgkmcnt(10)
	v_pk_fma_f32 v[16:17], v[98:99], v[144:145], v[16:17] op_sel_hi:[0,1,1]
	v_pk_fma_f32 v[18:19], v[98:99], v[146:147], v[18:19] op_sel_hi:[0,1,1]
	v_pk_fma_f32 v[20:21], v[98:99], v[148:149], v[20:21] op_sel_hi:[0,1,1]
	v_pk_fma_f32 v[22:23], v[98:99], v[150:151], v[22:23] op_sel_hi:[0,1,1]
	v_pk_fma_f32 v[24:25], v[98:99], v[152:153], v[24:25] op_sel_hi:[0,1,1]
	v_pk_fma_f32 v[26:27], v[98:99], v[154:155], v[26:27] op_sel_hi:[0,1,1]
	v_pk_fma_f32 v[28:29], v[98:99], v[156:157], v[28:29] op_sel_hi:[0,1,1]
	v_pk_fma_f32 v[30:31], v[98:99], v[158:159], v[30:31] op_sel_hi:[0,1,1]
	v_fmac_f32_e32 v2, v98, v192
	ds_read_b128 v[144:147], v5 offset:8640
	ds_read_b128 v[148:151], v5 offset:8656
	ds_read_b128 v[152:155], v5 offset:8672
	ds_read_b128 v[156:159], v5 offset:8688
	ds_read_b32 v192, v5 offset:8704
	s_waitcnt vmcnt(21) lgkmcnt(10)
	v_pk_fma_f32 v[16:17], v[100:101], v[160:161], v[16:17] op_sel_hi:[0,1,1]
	v_pk_fma_f32 v[18:19], v[100:101], v[162:163], v[18:19] op_sel_hi:[0,1,1]
	v_pk_fma_f32 v[20:21], v[100:101], v[164:165], v[20:21] op_sel_hi:[0,1,1]
	v_pk_fma_f32 v[22:23], v[100:101], v[166:167], v[22:23] op_sel_hi:[0,1,1]
	v_pk_fma_f32 v[24:25], v[100:101], v[168:169], v[24:25] op_sel_hi:[0,1,1]
	v_pk_fma_f32 v[26:27], v[100:101], v[170:171], v[26:27] op_sel_hi:[0,1,1]
	v_pk_fma_f32 v[28:29], v[100:101], v[172:173], v[28:29] op_sel_hi:[0,1,1]
	v_pk_fma_f32 v[30:31], v[100:101], v[174:175], v[30:31] op_sel_hi:[0,1,1]
	v_fmac_f32_e32 v2, v100, v193
	ds_read_b128 v[160:163], v5 offset:8720
	ds_read_b128 v[164:167], v5 offset:8736
	ds_read_b128 v[168:171], v5 offset:8752
	ds_read_b128 v[172:175], v5 offset:8768
	ds_read_b32 v193, v5 offset:8784
	s_waitcnt vmcnt(20) lgkmcnt(10)
	v_pk_fma_f32 v[16:17], v[102:103], v[176:177], v[16:17] op_sel_hi:[0,1,1]
	v_pk_fma_f32 v[18:19], v[102:103], v[178:179], v[18:19] op_sel_hi:[0,1,1]
	v_pk_fma_f32 v[20:21], v[102:103], v[180:181], v[20:21] op_sel_hi:[0,1,1]
	v_pk_fma_f32 v[22:23], v[102:103], v[182:183], v[22:23] op_sel_hi:[0,1,1]
	v_pk_fma_f32 v[24:25], v[102:103], v[184:185], v[24:25] op_sel_hi:[0,1,1]
	v_pk_fma_f32 v[26:27], v[102:103], v[186:187], v[26:27] op_sel_hi:[0,1,1]
	v_pk_fma_f32 v[28:29], v[102:103], v[188:189], v[28:29] op_sel_hi:[0,1,1]
	v_pk_fma_f32 v[30:31], v[102:103], v[190:191], v[30:31] op_sel_hi:[0,1,1]
	v_fmac_f32_e32 v2, v102, v194
	ds_read_b128 v[176:179], v5 offset:8800
	ds_read_b128 v[180:183], v5 offset:8816
	ds_read_b128 v[184:187], v5 offset:8832
	ds_read_b128 v[188:191], v5 offset:8848
	ds_read_b32 v194, v5 offset:8864
	s_waitcnt vmcnt(19) lgkmcnt(10)
	v_pk_fma_f32 v[16:17], v[104:105], v[144:145], v[16:17] op_sel_hi:[0,1,1]
	v_pk_fma_f32 v[18:19], v[104:105], v[146:147], v[18:19] op_sel_hi:[0,1,1]
	v_pk_fma_f32 v[20:21], v[104:105], v[148:149], v[20:21] op_sel_hi:[0,1,1]
	v_pk_fma_f32 v[22:23], v[104:105], v[150:151], v[22:23] op_sel_hi:[0,1,1]
	v_pk_fma_f32 v[24:25], v[104:105], v[152:153], v[24:25] op_sel_hi:[0,1,1]
	v_pk_fma_f32 v[26:27], v[104:105], v[154:155], v[26:27] op_sel_hi:[0,1,1]
	v_pk_fma_f32 v[28:29], v[104:105], v[156:157], v[28:29] op_sel_hi:[0,1,1]
	v_pk_fma_f32 v[30:31], v[104:105], v[158:159], v[30:31] op_sel_hi:[0,1,1]
	v_fmac_f32_e32 v2, v104, v192
	ds_read_b128 v[144:147], v5 offset:8880
	ds_read_b128 v[148:151], v5 offset:8896
	ds_read_b128 v[152:155], v5 offset:8912
	ds_read_b128 v[156:159], v5 offset:8928
	ds_read_b32 v192, v5 offset:8944
	s_waitcnt vmcnt(18) lgkmcnt(10)
	v_pk_fma_f32 v[16:17], v[106:107], v[160:161], v[16:17] op_sel_hi:[0,1,1]
	v_pk_fma_f32 v[18:19], v[106:107], v[162:163], v[18:19] op_sel_hi:[0,1,1]
	v_pk_fma_f32 v[20:21], v[106:107], v[164:165], v[20:21] op_sel_hi:[0,1,1]
	v_pk_fma_f32 v[22:23], v[106:107], v[166:167], v[22:23] op_sel_hi:[0,1,1]
	v_pk_fma_f32 v[24:25], v[106:107], v[168:169], v[24:25] op_sel_hi:[0,1,1]
	v_pk_fma_f32 v[26:27], v[106:107], v[170:171], v[26:27] op_sel_hi:[0,1,1]
	v_pk_fma_f32 v[28:29], v[106:107], v[172:173], v[28:29] op_sel_hi:[0,1,1]
	v_pk_fma_f32 v[30:31], v[106:107], v[174:175], v[30:31] op_sel_hi:[0,1,1]
	v_fmac_f32_e32 v2, v106, v193
	ds_read_b128 v[160:163], v5 offset:8960
	ds_read_b128 v[164:167], v5 offset:8976
	ds_read_b128 v[168:171], v5 offset:8992
	ds_read_b128 v[172:175], v5 offset:9008
	ds_read_b32 v193, v5 offset:9024
	s_waitcnt vmcnt(17) lgkmcnt(10)
	v_pk_fma_f32 v[16:17], v[108:109], v[176:177], v[16:17] op_sel_hi:[0,1,1]
	v_pk_fma_f32 v[18:19], v[108:109], v[178:179], v[18:19] op_sel_hi:[0,1,1]
	v_pk_fma_f32 v[20:21], v[108:109], v[180:181], v[20:21] op_sel_hi:[0,1,1]
	v_pk_fma_f32 v[22:23], v[108:109], v[182:183], v[22:23] op_sel_hi:[0,1,1]
	v_pk_fma_f32 v[24:25], v[108:109], v[184:185], v[24:25] op_sel_hi:[0,1,1]
	v_pk_fma_f32 v[26:27], v[108:109], v[186:187], v[26:27] op_sel_hi:[0,1,1]
	v_pk_fma_f32 v[28:29], v[108:109], v[188:189], v[28:29] op_sel_hi:[0,1,1]
	v_pk_fma_f32 v[30:31], v[108:109], v[190:191], v[30:31] op_sel_hi:[0,1,1]
	v_fmac_f32_e32 v2, v108, v194
	ds_read_b128 v[176:179], v5 offset:9040
	ds_read_b128 v[180:183], v5 offset:9056
	ds_read_b128 v[184:187], v5 offset:9072
	ds_read_b128 v[188:191], v5 offset:9088
	ds_read_b32 v194, v5 offset:9104
	s_waitcnt vmcnt(16) lgkmcnt(10)
	v_pk_fma_f32 v[16:17], v[110:111], v[144:145], v[16:17] op_sel_hi:[0,1,1]
	v_pk_fma_f32 v[18:19], v[110:111], v[146:147], v[18:19] op_sel_hi:[0,1,1]
	v_pk_fma_f32 v[20:21], v[110:111], v[148:149], v[20:21] op_sel_hi:[0,1,1]
	v_pk_fma_f32 v[22:23], v[110:111], v[150:151], v[22:23] op_sel_hi:[0,1,1]
	v_pk_fma_f32 v[24:25], v[110:111], v[152:153], v[24:25] op_sel_hi:[0,1,1]
	v_pk_fma_f32 v[26:27], v[110:111], v[154:155], v[26:27] op_sel_hi:[0,1,1]
	v_pk_fma_f32 v[28:29], v[110:111], v[156:157], v[28:29] op_sel_hi:[0,1,1]
	v_pk_fma_f32 v[30:31], v[110:111], v[158:159], v[30:31] op_sel_hi:[0,1,1]
	v_fmac_f32_e32 v2, v110, v192
	ds_read_b128 v[144:147], v5 offset:9120
	ds_read_b128 v[148:151], v5 offset:9136
	ds_read_b128 v[152:155], v5 offset:9152
	ds_read_b128 v[156:159], v5 offset:9168
	ds_read_b32 v192, v5 offset:9184
	s_waitcnt vmcnt(15) lgkmcnt(10)
	v_pk_fma_f32 v[16:17], v[112:113], v[160:161], v[16:17] op_sel_hi:[0,1,1]
	v_pk_fma_f32 v[18:19], v[112:113], v[162:163], v[18:19] op_sel_hi:[0,1,1]
	v_pk_fma_f32 v[20:21], v[112:113], v[164:165], v[20:21] op_sel_hi:[0,1,1]
	v_pk_fma_f32 v[22:23], v[112:113], v[166:167], v[22:23] op_sel_hi:[0,1,1]
	v_pk_fma_f32 v[24:25], v[112:113], v[168:169], v[24:25] op_sel_hi:[0,1,1]
	v_pk_fma_f32 v[26:27], v[112:113], v[170:171], v[26:27] op_sel_hi:[0,1,1]
	v_pk_fma_f32 v[28:29], v[112:113], v[172:173], v[28:29] op_sel_hi:[0,1,1]
	v_pk_fma_f32 v[30:31], v[112:113], v[174:175], v[30:31] op_sel_hi:[0,1,1]
	v_fmac_f32_e32 v2, v112, v193
	ds_read_b128 v[160:163], v5 offset:9200
	ds_read_b128 v[164:167], v5 offset:9216
	ds_read_b128 v[168:171], v5 offset:9232
	ds_read_b128 v[172:175], v5 offset:9248
	ds_read_b32 v193, v5 offset:9264
	s_waitcnt vmcnt(14) lgkmcnt(10)
	v_pk_fma_f32 v[16:17], v[114:115], v[176:177], v[16:17] op_sel_hi:[0,1,1]
	v_pk_fma_f32 v[18:19], v[114:115], v[178:179], v[18:19] op_sel_hi:[0,1,1]
	v_pk_fma_f32 v[20:21], v[114:115], v[180:181], v[20:21] op_sel_hi:[0,1,1]
	v_pk_fma_f32 v[22:23], v[114:115], v[182:183], v[22:23] op_sel_hi:[0,1,1]
	v_pk_fma_f32 v[24:25], v[114:115], v[184:185], v[24:25] op_sel_hi:[0,1,1]
	v_pk_fma_f32 v[26:27], v[114:115], v[186:187], v[26:27] op_sel_hi:[0,1,1]
	v_pk_fma_f32 v[28:29], v[114:115], v[188:189], v[28:29] op_sel_hi:[0,1,1]
	v_pk_fma_f32 v[30:31], v[114:115], v[190:191], v[30:31] op_sel_hi:[0,1,1]
	v_fmac_f32_e32 v2, v114, v194
	ds_read_b128 v[176:179], v5 offset:9280
	ds_read_b128 v[180:183], v5 offset:9296
	ds_read_b128 v[184:187], v5 offset:9312
	ds_read_b128 v[188:191], v5 offset:9328
	ds_read_b32 v194, v5 offset:9344
	s_waitcnt vmcnt(13) lgkmcnt(10)
	v_pk_fma_f32 v[16:17], v[116:117], v[144:145], v[16:17] op_sel_hi:[0,1,1]
	v_pk_fma_f32 v[18:19], v[116:117], v[146:147], v[18:19] op_sel_hi:[0,1,1]
	v_pk_fma_f32 v[20:21], v[116:117], v[148:149], v[20:21] op_sel_hi:[0,1,1]
	v_pk_fma_f32 v[22:23], v[116:117], v[150:151], v[22:23] op_sel_hi:[0,1,1]
	v_pk_fma_f32 v[24:25], v[116:117], v[152:153], v[24:25] op_sel_hi:[0,1,1]
	v_pk_fma_f32 v[26:27], v[116:117], v[154:155], v[26:27] op_sel_hi:[0,1,1]
	v_pk_fma_f32 v[28:29], v[116:117], v[156:157], v[28:29] op_sel_hi:[0,1,1]
	v_pk_fma_f32 v[30:31], v[116:117], v[158:159], v[30:31] op_sel_hi:[0,1,1]
	v_fmac_f32_e32 v2, v116, v192
	ds_read_b128 v[144:147], v5 offset:9360
	ds_read_b128 v[148:151], v5 offset:9376
	ds_read_b128 v[152:155], v5 offset:9392
	ds_read_b128 v[156:159], v5 offset:9408
	ds_read_b32 v192, v5 offset:9424
	s_waitcnt vmcnt(12) lgkmcnt(10)
	v_pk_fma_f32 v[16:17], v[118:119], v[160:161], v[16:17] op_sel_hi:[0,1,1]
	v_pk_fma_f32 v[18:19], v[118:119], v[162:163], v[18:19] op_sel_hi:[0,1,1]
	v_pk_fma_f32 v[20:21], v[118:119], v[164:165], v[20:21] op_sel_hi:[0,1,1]
	v_pk_fma_f32 v[22:23], v[118:119], v[166:167], v[22:23] op_sel_hi:[0,1,1]
	v_pk_fma_f32 v[24:25], v[118:119], v[168:169], v[24:25] op_sel_hi:[0,1,1]
	v_pk_fma_f32 v[26:27], v[118:119], v[170:171], v[26:27] op_sel_hi:[0,1,1]
	v_pk_fma_f32 v[28:29], v[118:119], v[172:173], v[28:29] op_sel_hi:[0,1,1]
	v_pk_fma_f32 v[30:31], v[118:119], v[174:175], v[30:31] op_sel_hi:[0,1,1]
	v_fmac_f32_e32 v2, v118, v193
	ds_read_b128 v[160:163], v5 offset:9440
	ds_read_b128 v[164:167], v5 offset:9456
	ds_read_b128 v[168:171], v5 offset:9472
	ds_read_b128 v[172:175], v5 offset:9488
	ds_read_b32 v193, v5 offset:9504
	s_waitcnt vmcnt(11) lgkmcnt(10)
	v_pk_fma_f32 v[16:17], v[120:121], v[176:177], v[16:17] op_sel_hi:[0,1,1]
	v_pk_fma_f32 v[18:19], v[120:121], v[178:179], v[18:19] op_sel_hi:[0,1,1]
	v_pk_fma_f32 v[20:21], v[120:121], v[180:181], v[20:21] op_sel_hi:[0,1,1]
	v_pk_fma_f32 v[22:23], v[120:121], v[182:183], v[22:23] op_sel_hi:[0,1,1]
	v_pk_fma_f32 v[24:25], v[120:121], v[184:185], v[24:25] op_sel_hi:[0,1,1]
	v_pk_fma_f32 v[26:27], v[120:121], v[186:187], v[26:27] op_sel_hi:[0,1,1]
	v_pk_fma_f32 v[28:29], v[120:121], v[188:189], v[28:29] op_sel_hi:[0,1,1]
	v_pk_fma_f32 v[30:31], v[120:121], v[190:191], v[30:31] op_sel_hi:[0,1,1]
	v_fmac_f32_e32 v2, v120, v194
	ds_read_b128 v[176:179], v5 offset:9520
	ds_read_b128 v[180:183], v5 offset:9536
	ds_read_b128 v[184:187], v5 offset:9552
	ds_read_b128 v[188:191], v5 offset:9568
	ds_read_b32 v194, v5 offset:9584
	s_waitcnt vmcnt(10) lgkmcnt(10)
	v_pk_fma_f32 v[16:17], v[122:123], v[144:145], v[16:17] op_sel_hi:[0,1,1]
	v_pk_fma_f32 v[18:19], v[122:123], v[146:147], v[18:19] op_sel_hi:[0,1,1]
	v_pk_fma_f32 v[20:21], v[122:123], v[148:149], v[20:21] op_sel_hi:[0,1,1]
	v_pk_fma_f32 v[22:23], v[122:123], v[150:151], v[22:23] op_sel_hi:[0,1,1]
	v_pk_fma_f32 v[24:25], v[122:123], v[152:153], v[24:25] op_sel_hi:[0,1,1]
	v_pk_fma_f32 v[26:27], v[122:123], v[154:155], v[26:27] op_sel_hi:[0,1,1]
	v_pk_fma_f32 v[28:29], v[122:123], v[156:157], v[28:29] op_sel_hi:[0,1,1]
	v_pk_fma_f32 v[30:31], v[122:123], v[158:159], v[30:31] op_sel_hi:[0,1,1]
	v_fmac_f32_e32 v2, v122, v192
	ds_read_b128 v[144:147], v5 offset:9600
	ds_read_b128 v[148:151], v5 offset:9616
	ds_read_b128 v[152:155], v5 offset:9632
	ds_read_b128 v[156:159], v5 offset:9648
	ds_read_b32 v192, v5 offset:9664
	s_waitcnt vmcnt(9) lgkmcnt(10)
	v_pk_fma_f32 v[16:17], v[124:125], v[160:161], v[16:17] op_sel_hi:[0,1,1]
	v_pk_fma_f32 v[18:19], v[124:125], v[162:163], v[18:19] op_sel_hi:[0,1,1]
	v_pk_fma_f32 v[20:21], v[124:125], v[164:165], v[20:21] op_sel_hi:[0,1,1]
	v_pk_fma_f32 v[22:23], v[124:125], v[166:167], v[22:23] op_sel_hi:[0,1,1]
	v_pk_fma_f32 v[24:25], v[124:125], v[168:169], v[24:25] op_sel_hi:[0,1,1]
	v_pk_fma_f32 v[26:27], v[124:125], v[170:171], v[26:27] op_sel_hi:[0,1,1]
	v_pk_fma_f32 v[28:29], v[124:125], v[172:173], v[28:29] op_sel_hi:[0,1,1]
	v_pk_fma_f32 v[30:31], v[124:125], v[174:175], v[30:31] op_sel_hi:[0,1,1]
	v_fmac_f32_e32 v2, v124, v193
	ds_read_b128 v[160:163], v5 offset:9680
	ds_read_b128 v[164:167], v5 offset:9696
	ds_read_b128 v[168:171], v5 offset:9712
	ds_read_b128 v[172:175], v5 offset:9728
	ds_read_b32 v193, v5 offset:9744
	s_waitcnt vmcnt(8) lgkmcnt(10)
	v_pk_fma_f32 v[16:17], v[126:127], v[176:177], v[16:17] op_sel_hi:[0,1,1]
	v_pk_fma_f32 v[18:19], v[126:127], v[178:179], v[18:19] op_sel_hi:[0,1,1]
	v_pk_fma_f32 v[20:21], v[126:127], v[180:181], v[20:21] op_sel_hi:[0,1,1]
	v_pk_fma_f32 v[22:23], v[126:127], v[182:183], v[22:23] op_sel_hi:[0,1,1]
	v_pk_fma_f32 v[24:25], v[126:127], v[184:185], v[24:25] op_sel_hi:[0,1,1]
	v_pk_fma_f32 v[26:27], v[126:127], v[186:187], v[26:27] op_sel_hi:[0,1,1]
	v_pk_fma_f32 v[28:29], v[126:127], v[188:189], v[28:29] op_sel_hi:[0,1,1]
	v_pk_fma_f32 v[30:31], v[126:127], v[190:191], v[30:31] op_sel_hi:[0,1,1]
	v_fmac_f32_e32 v2, v126, v194
	ds_read_b128 v[176:179], v5 offset:9760
	ds_read_b128 v[180:183], v5 offset:9776
	ds_read_b128 v[184:187], v5 offset:9792
	ds_read_b128 v[188:191], v5 offset:9808
	ds_read_b32 v194, v5 offset:9824
	s_waitcnt vmcnt(7) lgkmcnt(10)
	v_pk_fma_f32 v[16:17], v[128:129], v[144:145], v[16:17] op_sel_hi:[0,1,1]
	v_pk_fma_f32 v[18:19], v[128:129], v[146:147], v[18:19] op_sel_hi:[0,1,1]
	v_pk_fma_f32 v[20:21], v[128:129], v[148:149], v[20:21] op_sel_hi:[0,1,1]
	v_pk_fma_f32 v[22:23], v[128:129], v[150:151], v[22:23] op_sel_hi:[0,1,1]
	v_pk_fma_f32 v[24:25], v[128:129], v[152:153], v[24:25] op_sel_hi:[0,1,1]
	v_pk_fma_f32 v[26:27], v[128:129], v[154:155], v[26:27] op_sel_hi:[0,1,1]
	v_pk_fma_f32 v[28:29], v[128:129], v[156:157], v[28:29] op_sel_hi:[0,1,1]
	v_pk_fma_f32 v[30:31], v[128:129], v[158:159], v[30:31] op_sel_hi:[0,1,1]
	v_fmac_f32_e32 v2, v128, v192
	ds_read_b128 v[144:147], v5 offset:9840
	ds_read_b128 v[148:151], v5 offset:9856
	ds_read_b128 v[152:155], v5 offset:9872
	ds_read_b128 v[156:159], v5 offset:9888
	ds_read_b32 v192, v5 offset:9904
	s_waitcnt vmcnt(6) lgkmcnt(10)
	v_pk_fma_f32 v[16:17], v[130:131], v[160:161], v[16:17] op_sel_hi:[0,1,1]
	v_pk_fma_f32 v[18:19], v[130:131], v[162:163], v[18:19] op_sel_hi:[0,1,1]
	v_pk_fma_f32 v[20:21], v[130:131], v[164:165], v[20:21] op_sel_hi:[0,1,1]
	v_pk_fma_f32 v[22:23], v[130:131], v[166:167], v[22:23] op_sel_hi:[0,1,1]
	v_pk_fma_f32 v[24:25], v[130:131], v[168:169], v[24:25] op_sel_hi:[0,1,1]
	v_pk_fma_f32 v[26:27], v[130:131], v[170:171], v[26:27] op_sel_hi:[0,1,1]
	v_pk_fma_f32 v[28:29], v[130:131], v[172:173], v[28:29] op_sel_hi:[0,1,1]
	v_pk_fma_f32 v[30:31], v[130:131], v[174:175], v[30:31] op_sel_hi:[0,1,1]
	v_fmac_f32_e32 v2, v130, v193
	ds_read_b128 v[160:163], v5 offset:9920
	ds_read_b128 v[164:167], v5 offset:9936
	ds_read_b128 v[168:171], v5 offset:9952
	ds_read_b128 v[172:175], v5 offset:9968
	ds_read_b32 v193, v5 offset:9984
	s_waitcnt vmcnt(5) lgkmcnt(10)
	v_pk_fma_f32 v[16:17], v[132:133], v[176:177], v[16:17] op_sel_hi:[0,1,1]
	v_pk_fma_f32 v[18:19], v[132:133], v[178:179], v[18:19] op_sel_hi:[0,1,1]
	v_pk_fma_f32 v[20:21], v[132:133], v[180:181], v[20:21] op_sel_hi:[0,1,1]
	v_pk_fma_f32 v[22:23], v[132:133], v[182:183], v[22:23] op_sel_hi:[0,1,1]
	v_pk_fma_f32 v[24:25], v[132:133], v[184:185], v[24:25] op_sel_hi:[0,1,1]
	v_pk_fma_f32 v[26:27], v[132:133], v[186:187], v[26:27] op_sel_hi:[0,1,1]
	v_pk_fma_f32 v[28:29], v[132:133], v[188:189], v[28:29] op_sel_hi:[0,1,1]
	v_pk_fma_f32 v[30:31], v[132:133], v[190:191], v[30:31] op_sel_hi:[0,1,1]
	v_fmac_f32_e32 v2, v132, v194
	ds_read_b128 v[176:179], v5 offset:10000
	ds_read_b128 v[180:183], v5 offset:10016
	ds_read_b128 v[184:187], v5 offset:10032
	ds_read_b128 v[188:191], v5 offset:10048
	ds_read_b32 v194, v5 offset:10064
	s_waitcnt vmcnt(4) lgkmcnt(10)
	v_pk_fma_f32 v[16:17], v[134:135], v[144:145], v[16:17] op_sel_hi:[0,1,1]
	v_pk_fma_f32 v[18:19], v[134:135], v[146:147], v[18:19] op_sel_hi:[0,1,1]
	v_pk_fma_f32 v[20:21], v[134:135], v[148:149], v[20:21] op_sel_hi:[0,1,1]
	v_pk_fma_f32 v[22:23], v[134:135], v[150:151], v[22:23] op_sel_hi:[0,1,1]
	v_pk_fma_f32 v[24:25], v[134:135], v[152:153], v[24:25] op_sel_hi:[0,1,1]
	v_pk_fma_f32 v[26:27], v[134:135], v[154:155], v[26:27] op_sel_hi:[0,1,1]
	v_pk_fma_f32 v[28:29], v[134:135], v[156:157], v[28:29] op_sel_hi:[0,1,1]
	v_pk_fma_f32 v[30:31], v[134:135], v[158:159], v[30:31] op_sel_hi:[0,1,1]
	v_fmac_f32_e32 v2, v134, v192
	ds_read_b128 v[144:147], v5 offset:10080
	ds_read_b128 v[148:151], v5 offset:10096
	ds_read_b128 v[152:155], v5 offset:10112
	ds_read_b128 v[156:159], v5 offset:10128
	ds_read_b32 v192, v5 offset:10144
	s_waitcnt vmcnt(3) lgkmcnt(10)
	v_pk_fma_f32 v[16:17], v[136:137], v[160:161], v[16:17] op_sel_hi:[0,1,1]
	v_pk_fma_f32 v[18:19], v[136:137], v[162:163], v[18:19] op_sel_hi:[0,1,1]
	v_pk_fma_f32 v[20:21], v[136:137], v[164:165], v[20:21] op_sel_hi:[0,1,1]
	v_pk_fma_f32 v[22:23], v[136:137], v[166:167], v[22:23] op_sel_hi:[0,1,1]
	v_pk_fma_f32 v[24:25], v[136:137], v[168:169], v[24:25] op_sel_hi:[0,1,1]
	v_pk_fma_f32 v[26:27], v[136:137], v[170:171], v[26:27] op_sel_hi:[0,1,1]
	v_pk_fma_f32 v[28:29], v[136:137], v[172:173], v[28:29] op_sel_hi:[0,1,1]
	v_pk_fma_f32 v[30:31], v[136:137], v[174:175], v[30:31] op_sel_hi:[0,1,1]
	v_fmac_f32_e32 v2, v136, v193
	ds_read_b128 v[160:163], v5 offset:10160
	ds_read_b128 v[164:167], v5 offset:10176
	ds_read_b128 v[168:171], v5 offset:10192
	ds_read_b128 v[172:175], v5 offset:10208
	ds_read_b32 v193, v5 offset:10224
	s_waitcnt vmcnt(2) lgkmcnt(10)
	v_pk_fma_f32 v[16:17], v[138:139], v[176:177], v[16:17] op_sel_hi:[0,1,1]
	v_pk_fma_f32 v[18:19], v[138:139], v[178:179], v[18:19] op_sel_hi:[0,1,1]
	v_pk_fma_f32 v[20:21], v[138:139], v[180:181], v[20:21] op_sel_hi:[0,1,1]
	v_pk_fma_f32 v[22:23], v[138:139], v[182:183], v[22:23] op_sel_hi:[0,1,1]
	v_pk_fma_f32 v[24:25], v[138:139], v[184:185], v[24:25] op_sel_hi:[0,1,1]
	v_pk_fma_f32 v[26:27], v[138:139], v[186:187], v[26:27] op_sel_hi:[0,1,1]
	v_pk_fma_f32 v[28:29], v[138:139], v[188:189], v[28:29] op_sel_hi:[0,1,1]
	v_pk_fma_f32 v[30:31], v[138:139], v[190:191], v[30:31] op_sel_hi:[0,1,1]
	v_fmac_f32_e32 v2, v138, v194
	s_waitcnt vmcnt(1) lgkmcnt(5)
	v_pk_fma_f32 v[16:17], v[140:141], v[144:145], v[16:17] op_sel_hi:[0,1,1]
	v_pk_fma_f32 v[18:19], v[140:141], v[146:147], v[18:19] op_sel_hi:[0,1,1]
	v_pk_fma_f32 v[20:21], v[140:141], v[148:149], v[20:21] op_sel_hi:[0,1,1]
	v_pk_fma_f32 v[22:23], v[140:141], v[150:151], v[22:23] op_sel_hi:[0,1,1]
	v_pk_fma_f32 v[24:25], v[140:141], v[152:153], v[24:25] op_sel_hi:[0,1,1]
	v_pk_fma_f32 v[26:27], v[140:141], v[154:155], v[26:27] op_sel_hi:[0,1,1]
	v_pk_fma_f32 v[28:29], v[140:141], v[156:157], v[28:29] op_sel_hi:[0,1,1]
	v_pk_fma_f32 v[30:31], v[140:141], v[158:159], v[30:31] op_sel_hi:[0,1,1]
	v_fmac_f32_e32 v2, v140, v192
	s_waitcnt vmcnt(0) lgkmcnt(0)
	v_pk_fma_f32 v[16:17], v[142:143], v[160:161], v[16:17] op_sel_hi:[0,1,1]
	v_pk_fma_f32 v[18:19], v[142:143], v[162:163], v[18:19] op_sel_hi:[0,1,1]
	v_pk_fma_f32 v[20:21], v[142:143], v[164:165], v[20:21] op_sel_hi:[0,1,1]
	v_pk_fma_f32 v[22:23], v[142:143], v[166:167], v[22:23] op_sel_hi:[0,1,1]
	v_pk_fma_f32 v[24:25], v[142:143], v[168:169], v[24:25] op_sel_hi:[0,1,1]
	v_pk_fma_f32 v[26:27], v[142:143], v[170:171], v[26:27] op_sel_hi:[0,1,1]
	v_pk_fma_f32 v[28:29], v[142:143], v[172:173], v[28:29] op_sel_hi:[0,1,1]
	v_pk_fma_f32 v[30:31], v[142:143], v[174:175], v[30:31] op_sel_hi:[0,1,1]
	v_fmac_f32_e32 v2, v142, v193
	s_movk_i32 s1, 0x80
	s_cmpk_eq_i32 s1, 0x80
	s_movk_i32 s1, 0x440
	v_lshl_add_u32 v5, v4, 2, s37
	v_cmp_gt_i32_e32 vcc, s1, v8
	ds_write2st64_b32 v5, v16, v17 offset1:1
	ds_write2st64_b32 v5, v18, v19 offset0:2 offset1:3
	ds_write2st64_b32 v5, v20, v21 offset0:4 offset1:5
	ds_write2st64_b32 v5, v22, v23 offset0:6 offset1:7
	ds_write2st64_b32 v5, v24, v25 offset0:8 offset1:9
	ds_write2st64_b32 v5, v26, v27 offset0:10 offset1:11
	ds_write2st64_b32 v5, v28, v29 offset0:12 offset1:13
	ds_write2st64_b32 v5, v30, v31 offset0:14 offset1:15
	ds_write_b32 v5, v2 offset:4096
	s_waitcnt lgkmcnt(0)
	s_barrier
	s_and_saveexec_b64 s[8:9], vcc
	s_cbranch_execz .LBB0_5
	s_mul_i32 s1, s0, 0x1800
	s_add_i32 s6, s1, s2
	v_and_b32_e32 v7, 63, v4
	s_add_u32 s2, s20, s4
	v_or_b32_e32 v14, s6, v7
	v_readlane_b32 s64, v239, 44
	s_addc_u32 s3, s21, s5
	v_lshlrev_b32_e32 v2, 2, v7
	v_ashrrev_i32_e32 v15, 31, v14
	v_readlane_b32 s74, v239, 54
	v_readlane_b32 s75, v239, 55
	s_mul_hi_i32 s1, s0, 17
	s_mul_i32 s0, s0, 17
	v_or_b32_e32 v5, 0x14000, v2
	v_lshl_add_u64 v[14:15], v[14:15], 2, s[74:75]
	v_lshl_add_u64 v[16:17], s[2:3], 0, v[2:3]
	s_mov_b64 s[2:3], 0
	v_mov_b32_e32 v2, v8
	v_readlane_b32 s65, v239, 45
	v_readlane_b32 s66, v239, 46
	v_readlane_b32 s67, v239, 47
	v_readlane_b32 s68, v239, 48
	v_readlane_b32 s69, v239, 49
	v_readlane_b32 s70, v239, 50
	v_readlane_b32 s71, v239, 51
	v_readlane_b32 s72, v239, 52
	v_readlane_b32 s73, v239, 53
	v_readlane_b32 s76, v239, 56
	v_readlane_b32 s77, v239, 57
	v_readlane_b32 s78, v239, 58
	v_readlane_b32 s79, v239, 59
